# grid barriers: waiters poll the cross-XCD arrival counter (TOP >= (gen+1)*nx) directly instead of the release generation word, removing one atomic round trip + one add from the release path
# speedup vs baseline: 1.0125x; 1.0125x over previous
.LBB0_164:
	s_or_b64 exec, exec, s[10:11]
	v_cvt_f32_u32_e32 v4, v2
	s_waitcnt vmcnt(0)
	v_readfirstlane_b32 s8, v3
	v_sub_u32_e32 v3, 0, v2
	v_rcp_iflag_f32_e32 v4, v4
	v_add_u32_e32 v5, s8, v1
	v_mul_f32_e32 v4, 0x4f7ffffe, v4
	v_cvt_u32_f32_e32 v4, v4
	v_mul_lo_u32 v1, v3, v4
	v_mul_hi_u32 v1, v4, v1
	v_add_u32_e32 v1, v4, v1
	v_mul_hi_u32 v1, v5, v1
	v_mul_lo_u32 v3, v1, v2
	v_sub_u32_e32 v3, v5, v3
	v_add_u32_e32 v4, 1, v1
	v_cmp_ge_u32_e32 vcc, v3, v2
	s_nop 1
	v_cndmask_b32_e32 v1, v1, v4, vcc
	v_sub_u32_e32 v4, v3, v2
	v_cndmask_b32_e32 v3, v3, v4, vcc
	v_add_u32_e32 v4, 1, v1
	v_cmp_ge_u32_e32 vcc, v3, v2
	v_add_u32_e32 v3, 1, v5
	s_nop 0
	v_cndmask_b32_e32 v1, v1, v4, vcc
	v_mul_lo_u32 v4, v2, v1
	v_add_u32_e32 v2, v4, v2
	v_cmp_ne_u32_e32 vcc, v3, v2
	s_and_saveexec_b64 s[8:9], vcc
	s_xor_b64 s[8:9], exec, s[8:9]
	s_cbranch_execz .LBB0_178
	s_waitcnt lgkmcnt(0)
	v_mad_u32_u24 v3, v1, v0, v0
	v_mov_b32_e32 v0, 0x3000
	global_load_dword v0, v0, s[54:55] offset:1024 sc1
	s_add_u32 s12, s54, 0x3400
	s_addc_u32 s13, s55, 0
	s_waitcnt vmcnt(0)
	v_cmp_lt_u32_e32 vcc, v0, v3
	s_and_saveexec_b64 s[10:11], vcc
	s_cbranch_execz .LBB0_177
	s_mov_b32 s24, 1
	s_mov_b64 s[14:15], 0
	v_mov_b32_e32 v0, 0
	s_branch .LBB0_168

.LBB0_172:
	global_load_dword v2, v0, s[12:13] sc1
	s_add_i32 s24, s24, 1
	s_mov_b64 s[20:21], -1
	s_waitcnt vmcnt(0)
	v_cmp_ge_u32_e32 vcc, v2, v3
	s_orn2_b64 s[18:19], vcc, exec
	s_branch .LBB0_167

.LBB0_181:
	s_or_b64 exec, exec, s[10:11]
	v_cvt_f32_u32_e32 v3, v0
	s_waitcnt vmcnt(0)
	v_readfirstlane_b32 s8, v2
	s_add_u32 s10, s54, 0x3500
	s_addc_u32 s11, s55, 0
	v_rcp_iflag_f32_e32 v3, v3
	v_add_u32_e32 v1, s8, v1
	v_add_u32_e32 v4, 1, v1
	s_mov_b64 s[12:13], -1
	v_mul_f32_e32 v2, 0x4f7ffffe, v3
	v_cvt_u32_f32_e32 v2, v2
	v_sub_u32_e32 v3, 0, v0
	v_mul_lo_u32 v3, v3, v2
	v_mul_hi_u32 v3, v2, v3
	v_add_u32_e32 v2, v2, v3
	v_mul_hi_u32 v2, v1, v2
	v_mul_lo_u32 v3, v2, v0
	v_sub_u32_e32 v1, v1, v3
	v_add_u32_e32 v5, 1, v2
	v_cmp_ge_u32_e32 vcc, v1, v0
	v_sub_u32_e32 v3, v1, v0
	s_nop 0
	v_cndmask_b32_e32 v2, v2, v5, vcc
	v_cndmask_b32_e32 v1, v1, v3, vcc
	v_add_u32_e32 v3, 1, v2
	v_cmp_ge_u32_e32 vcc, v1, v0
	s_nop 1
	v_cndmask_b32_e32 v2, v2, v3, vcc
	v_mul_lo_u32 v1, v0, v2
	v_add_u32_e32 v0, v1, v0
	v_cmp_ne_u32_e32 vcc, v4, v0
	v_mov_b32_e32 v3, v0
	v_mov_b64_e32 v[0:1], s[10:11]
	s_and_saveexec_b64 s[8:9], vcc
	s_cbranch_execz .LBB0_193
	v_mov_b32_e32 v0, 0
	global_load_dword v1, v0, s[10:11] offset:-256 sc1
	s_mov_b64 s[16:17], 0
	s_waitcnt vmcnt(0)
	v_cmp_lt_u32_e32 vcc, v1, v3
	s_and_saveexec_b64 s[14:15], vcc
	s_cbranch_execz .LBB0_192
	s_add_u32 s12, s54, 0x200
	s_addc_u32 s13, s55, 0
	s_mov_b32 s26, 1
	s_branch .LBB0_185

.LBB0_189:
	global_load_dword v1, v0, s[10:11] offset:-256 sc1
	s_add_i32 s26, s26, 1
	s_mov_b64 s[20:21], -1
	s_waitcnt vmcnt(0)
	v_cmp_ge_u32_e32 vcc, v1, v3
	s_orn2_b64 s[24:25], vcc, exec
	s_branch .LBB0_184

.Lph217_w:
	s_nop 0
	s_nop 0
	s_nop 0
	s_waitcnt vmcnt(8)
	s_waitcnt lgkmcnt(0)
	s_setprio 1
	s_barrier
	v_mfma_f32_16x16x32_bf16 v[124:127], v[146:149], v[186:189], v[124:127]
	v_mfma_f32_16x16x32_bf16 v[120:123], v[162:165], v[186:189], v[120:123]
	v_mfma_f32_16x16x32_bf16 v[108:111], v[146:149], v[194:197], v[108:111]
	v_mfma_f32_16x16x32_bf16 v[104:107], v[162:165], v[194:197], v[104:107]
	v_mfma_f32_16x16x32_bf16 v[92:95], v[146:149], v[202:205], v[92:95]
	v_mfma_f32_16x16x32_bf16 v[88:91], v[162:165], v[202:205], v[88:91]
	v_mfma_f32_16x16x32_bf16 v[76:79], v[146:149], v[210:213], v[76:79]
	v_mfma_f32_16x16x32_bf16 v[72:75], v[162:165], v[210:213], v[72:75]
	v_mfma_f32_16x16x32_bf16 v[124:127], v[158:161], v[190:193], v[124:127]
	v_mfma_f32_16x16x32_bf16 v[120:123], v[166:169], v[190:193], v[120:123]
	v_mfma_f32_16x16x32_bf16 v[108:111], v[158:161], v[198:201], v[108:111]
	v_mfma_f32_16x16x32_bf16 v[104:107], v[166:169], v[198:201], v[104:107]
	v_mfma_f32_16x16x32_bf16 v[92:95], v[158:161], v[206:209], v[92:95]
	v_mfma_f32_16x16x32_bf16 v[88:91], v[166:169], v[206:209], v[88:91]
	v_mfma_f32_16x16x32_bf16 v[76:79], v[158:161], v[214:217], v[76:79]
	v_mfma_f32_16x16x32_bf16 v[72:75], v[166:169], v[214:217], v[72:75]
	s_setprio 0
	s_setprio 1
	v_mfma_f32_16x16x32_bf16 v[116:119], v[170:173], v[186:189], v[116:119]
	v_mfma_f32_16x16x32_bf16 v[112:115], v[178:181], v[186:189], v[112:115]
	v_mfma_f32_16x16x32_bf16 v[100:103], v[170:173], v[194:197], v[100:103]
	v_mfma_f32_16x16x32_bf16 v[96:99], v[178:181], v[194:197], v[96:99]
	v_mfma_f32_16x16x32_bf16 v[84:87], v[170:173], v[202:205], v[84:87]
	v_mfma_f32_16x16x32_bf16 v[80:83], v[178:181], v[202:205], v[80:83]
	v_mfma_f32_16x16x32_bf16 v[68:71], v[170:173], v[210:213], v[68:71]
	v_mfma_f32_16x16x32_bf16 v[64:67], v[178:181], v[210:213], v[64:67]
	v_mfma_f32_16x16x32_bf16 v[116:119], v[174:177], v[190:193], v[116:119]
	v_mfma_f32_16x16x32_bf16 v[112:115], v[182:185], v[190:193], v[112:115]
	v_mfma_f32_16x16x32_bf16 v[100:103], v[174:177], v[198:201], v[100:103]
	v_mfma_f32_16x16x32_bf16 v[96:99], v[182:185], v[198:201], v[96:99]
	v_mfma_f32_16x16x32_bf16 v[84:87], v[174:177], v[206:209], v[84:87]
	v_mfma_f32_16x16x32_bf16 v[80:83], v[182:185], v[206:209], v[80:83]
	v_mfma_f32_16x16x32_bf16 v[68:71], v[174:177], v[214:217], v[68:71]
	v_mfma_f32_16x16x32_bf16 v[64:67], v[182:185], v[214:217], v[64:67]
	s_barrier
	s_setprio 0
	s_add_i32 s72, s65, s43
	v_lshl_add_u64 v[150:151], s[36:37], 0, v[130:131]
	s_mov_b32 m0, s72
	s_nop 0
	global_load_lds_dwordx4 v[150:151], off
	s_add_i32 m0, s72, 0x2000
	s_add_u32 s72, s36, 0x40000
	v_lshl_add_u64 v[218:219], s[36:37], 0, v[134:135]
	s_addc_u32 s73, s37, 0
	s_add_i32 s74, s67, s43
	global_load_lds_dwordx4 v[218:219], off
	v_lshl_add_u64 v[220:221], s[72:73], 0, v[130:131]
	s_mov_b32 m0, s74
	v_lshl_add_u64 v[222:223], s[38:39], 0, v[132:133]
	global_load_lds_dwordx4 v[220:221], off
	v_lshl_add_u64 v[220:221], s[72:73], 0, v[134:135]
	s_add_i32 m0, s74, 0x2000
	s_nop 0
	global_load_lds_dwordx4 v[220:221], off
	v_lshl_add_u64 v[220:221], s[38:39], 0, v[128:129]
	s_mov_b32 m0, s31
	s_nop 0
	global_load_lds_dwordx4 v[220:221], off
	s_mov_b32 m0, s46
	s_nop 0
	global_load_lds_dwordx4 v[222:223], off
	ds_read_b128 v[186:189], v157 offset:16384
	ds_read_b128 v[190:193], v157 offset:17408
	ds_read_b128 v[194:197], v157 offset:18432
	ds_read_b128 v[198:201], v157 offset:19456
	ds_read_b128 v[202:205], v157 offset:20480
	ds_read_b128 v[206:209], v157 offset:21504
	ds_read_b128 v[210:213], v157 offset:22528
	ds_read_b128 v[214:217], v157 offset:23552
	s_nop 0
	s_waitcnt vmcnt(8)
	s_waitcnt lgkmcnt(0)
	s_setprio 1
	s_barrier
	v_mfma_f32_16x16x32_bf16 v[60:63], v[146:149], v[186:189], v[60:63]
	v_mfma_f32_16x16x32_bf16 v[56:59], v[162:165], v[186:189], v[56:59]
	v_mfma_f32_16x16x32_bf16 v[44:47], v[146:149], v[194:197], v[44:47]
	v_mfma_f32_16x16x32_bf16 v[40:43], v[162:165], v[194:197], v[40:43]
	v_mfma_f32_16x16x32_bf16 v[28:31], v[146:149], v[202:205], v[28:31]
	v_mfma_f32_16x16x32_bf16 v[24:27], v[162:165], v[202:205], v[24:27]
	v_mfma_f32_16x16x32_bf16 v[12:15], v[146:149], v[210:213], v[12:15]
	v_mfma_f32_16x16x32_bf16 v[8:11], v[162:165], v[210:213], v[8:11]
	v_mfma_f32_16x16x32_bf16 v[60:63], v[158:161], v[190:193], v[60:63]
	v_mfma_f32_16x16x32_bf16 v[56:59], v[166:169], v[190:193], v[56:59]
	v_mfma_f32_16x16x32_bf16 v[44:47], v[158:161], v[198:201], v[44:47]
	v_mfma_f32_16x16x32_bf16 v[40:43], v[166:169], v[198:201], v[40:43]
	v_mfma_f32_16x16x32_bf16 v[28:31], v[158:161], v[206:209], v[28:31]
	v_mfma_f32_16x16x32_bf16 v[24:27], v[166:169], v[206:209], v[24:27]
	v_mfma_f32_16x16x32_bf16 v[12:15], v[158:161], v[214:217], v[12:15]
	v_mfma_f32_16x16x32_bf16 v[8:11], v[166:169], v[214:217], v[8:11]
	s_setprio 0
	s_setprio 1
	v_mfma_f32_16x16x32_bf16 v[52:55], v[170:173], v[186:189], v[52:55]
	v_mfma_f32_16x16x32_bf16 v[48:51], v[178:181], v[186:189], v[48:51]
	v_mfma_f32_16x16x32_bf16 v[36:39], v[170:173], v[194:197], v[36:39]
	v_mfma_f32_16x16x32_bf16 v[32:35], v[178:181], v[194:197], v[32:35]
	v_mfma_f32_16x16x32_bf16 v[20:23], v[170:173], v[202:205], v[20:23]
	v_mfma_f32_16x16x32_bf16 v[16:19], v[178:181], v[202:205], v[16:19]
	v_mfma_f32_16x16x32_bf16 v[4:7], v[170:173], v[210:213], v[4:7]
	v_mfma_f32_16x16x32_bf16 v[0:3], v[178:181], v[210:213], v[0:3]
	v_mfma_f32_16x16x32_bf16 v[52:55], v[174:177], v[190:193], v[52:55]
	v_mfma_f32_16x16x32_bf16 v[48:51], v[182:185], v[190:193], v[48:51]
	v_mfma_f32_16x16x32_bf16 v[36:39], v[174:177], v[198:201], v[36:39]
	v_mfma_f32_16x16x32_bf16 v[32:35], v[182:185], v[198:201], v[32:35]
	v_mfma_f32_16x16x32_bf16 v[20:23], v[174:177], v[206:209], v[20:23]
	v_mfma_f32_16x16x32_bf16 v[16:19], v[182:185], v[206:209], v[16:19]
	v_mfma_f32_16x16x32_bf16 v[4:7], v[174:177], v[214:217], v[4:7]
	v_mfma_f32_16x16x32_bf16 v[0:3], v[182:185], v[214:217], v[0:3]
	s_barrier
	s_setprio 0
	s_add_i32 s72, 0, 0x18000
	s_add_i32 s73, 0, 0x1c000
	s_add_u32 s38, s38, 0x40000
	s_addc_u32 s39, s39, 0
	s_mov_b32 m0, s47
	v_lshl_add_u64 v[224:225], s[38:39], 0, v[128:129]
	global_load_lds_dwordx4 v[224:225], off
	v_lshl_add_u64 v[224:225], s[38:39], 0, v[132:133]
	s_mov_b32 m0, s48
	s_nop 0
	global_load_lds_dwordx4 v[224:225], off
	v_add_u32_e32 v136, s72, v153
	ds_read_b128 v[146:149], v136
	ds_read_b128 v[158:161], v136 offset:1024
	ds_read_b128 v[162:165], v136 offset:2048
	ds_read_b128 v[166:169], v136 offset:3072
	v_add_u32_e32 v136, s73, v153
	ds_read_b128 v[170:173], v136
	ds_read_b128 v[174:177], v136 offset:1024
	ds_read_b128 v[178:181], v136 offset:2048
	ds_read_b128 v[182:185], v136 offset:3072
	ds_read_b128 v[186:189], v157 offset:32768
	ds_read_b128 v[190:193], v157 offset:33792
	ds_read_b128 v[194:197], v157 offset:34816
	ds_read_b128 v[198:201], v157 offset:35840
	ds_read_b128 v[202:205], v157 offset:36864
	ds_read_b128 v[206:209], v157 offset:37888
	ds_read_b128 v[210:213], v157 offset:38912
	ds_read_b128 v[214:217], v157 offset:39936
	s_waitcnt vmcnt(8)
	s_waitcnt lgkmcnt(0)
	s_setprio 1
	s_barrier
	v_mfma_f32_16x16x32_bf16 v[124:127], v[146:149], v[186:189], v[124:127]
	v_mfma_f32_16x16x32_bf16 v[120:123], v[162:165], v[186:189], v[120:123]
	v_mfma_f32_16x16x32_bf16 v[108:111], v[146:149], v[194:197], v[108:111]
	v_mfma_f32_16x16x32_bf16 v[104:107], v[162:165], v[194:197], v[104:107]
	v_mfma_f32_16x16x32_bf16 v[92:95], v[146:149], v[202:205], v[92:95]
	v_mfma_f32_16x16x32_bf16 v[88:91], v[162:165], v[202:205], v[88:91]
	v_mfma_f32_16x16x32_bf16 v[76:79], v[146:149], v[210:213], v[76:79]
	v_mfma_f32_16x16x32_bf16 v[72:75], v[162:165], v[210:213], v[72:75]
	v_mfma_f32_16x16x32_bf16 v[124:127], v[158:161], v[190:193], v[124:127]
	v_mfma_f32_16x16x32_bf16 v[120:123], v[166:169], v[190:193], v[120:123]
	v_mfma_f32_16x16x32_bf16 v[108:111], v[158:161], v[198:201], v[108:111]
	v_mfma_f32_16x16x32_bf16 v[104:107], v[166:169], v[198:201], v[104:107]
	v_mfma_f32_16x16x32_bf16 v[92:95], v[158:161], v[206:209], v[92:95]
	v_mfma_f32_16x16x32_bf16 v[88:91], v[166:169], v[206:209], v[88:91]
	v_mfma_f32_16x16x32_bf16 v[76:79], v[158:161], v[214:217], v[76:79]
	v_mfma_f32_16x16x32_bf16 v[72:75], v[166:169], v[214:217], v[72:75]
	s_setprio 0
	s_setprio 1
	v_mfma_f32_16x16x32_bf16 v[116:119], v[170:173], v[186:189], v[116:119]
	v_mfma_f32_16x16x32_bf16 v[112:115], v[178:181], v[186:189], v[112:115]
	v_mfma_f32_16x16x32_bf16 v[100:103], v[170:173], v[194:197], v[100:103]
	v_mfma_f32_16x16x32_bf16 v[96:99], v[178:181], v[194:197], v[96:99]
	v_mfma_f32_16x16x32_bf16 v[84:87], v[170:173], v[202:205], v[84:87]
	v_mfma_f32_16x16x32_bf16 v[80:83], v[178:181], v[202:205], v[80:83]
	v_mfma_f32_16x16x32_bf16 v[68:71], v[170:173], v[210:213], v[68:71]
	v_mfma_f32_16x16x32_bf16 v[64:67], v[178:181], v[210:213], v[64:67]
	v_mfma_f32_16x16x32_bf16 v[116:119], v[174:177], v[190:193], v[116:119]
	v_mfma_f32_16x16x32_bf16 v[112:115], v[182:185], v[190:193], v[112:115]
	v_mfma_f32_16x16x32_bf16 v[100:103], v[174:177], v[198:201], v[100:103]
	v_mfma_f32_16x16x32_bf16 v[96:99], v[182:185], v[198:201], v[96:99]
	v_mfma_f32_16x16x32_bf16 v[84:87], v[174:177], v[206:209], v[84:87]
	v_mfma_f32_16x16x32_bf16 v[80:83], v[182:185], v[206:209], v[80:83]
	v_mfma_f32_16x16x32_bf16 v[68:71], v[174:177], v[214:217], v[68:71]
	v_mfma_f32_16x16x32_bf16 v[64:67], v[182:185], v[214:217], v[64:67]
	s_barrier
	s_setprio 0
	s_add_i32 s38, s72, s43
	v_lshl_add_u64 v[150:151], v[150:151], 0, s[12:13]
	s_mov_b32 m0, s38
	s_nop 0
	global_load_lds_dwordx4 v[150:151], off
	s_add_i32 m0, s38, 0x2000
	s_add_u32 s36, s36, 0x40080
	v_lshl_add_u64 v[150:151], v[218:219], 0, s[12:13]
	s_addc_u32 s37, s37, 0
	s_add_i32 s38, s73, s43
	global_load_lds_dwordx4 v[150:151], off
	v_lshl_add_u64 v[150:151], s[36:37], 0, v[130:131]
	s_mov_b32 m0, s38
	s_nop 0
	global_load_lds_dwordx4 v[150:151], off
	v_lshl_add_u64 v[150:151], s[36:37], 0, v[134:135]
	s_add_i32 m0, s38, 0x2000
	s_nop 0
	global_load_lds_dwordx4 v[150:151], off
	v_lshl_add_u64 v[150:151], v[220:221], 0, s[12:13]
	s_mov_b32 m0, s60
	s_nop 0
	global_load_lds_dwordx4 v[150:151], off
	v_lshl_add_u64 v[150:151], v[222:223], 0, s[12:13]
	s_mov_b32 m0, s61
	s_nop 0
	global_load_lds_dwordx4 v[150:151], off
	ds_read_b128 v[186:189], v157 offset:49152
	ds_read_b128 v[190:193], v157 offset:50176
	ds_read_b128 v[194:197], v157 offset:51200
	ds_read_b128 v[198:201], v157 offset:52224
	ds_read_b128 v[202:205], v157 offset:53248
	ds_read_b128 v[206:209], v157 offset:54272
	ds_read_b128 v[210:213], v157 offset:55296
	ds_read_b128 v[214:217], v157 offset:56320
	s_waitcnt vmcnt(8)
	s_waitcnt lgkmcnt(0)
	s_setprio 1
	s_barrier
	v_mfma_f32_16x16x32_bf16 v[60:63], v[146:149], v[186:189], v[60:63]
	v_mfma_f32_16x16x32_bf16 v[56:59], v[162:165], v[186:189], v[56:59]
	v_mfma_f32_16x16x32_bf16 v[44:47], v[146:149], v[194:197], v[44:47]
	v_mfma_f32_16x16x32_bf16 v[40:43], v[162:165], v[194:197], v[40:43]
	v_mfma_f32_16x16x32_bf16 v[28:31], v[146:149], v[202:205], v[28:31]
	v_mfma_f32_16x16x32_bf16 v[24:27], v[162:165], v[202:205], v[24:27]
	v_mfma_f32_16x16x32_bf16 v[12:15], v[146:149], v[210:213], v[12:15]
	v_mfma_f32_16x16x32_bf16 v[8:11], v[162:165], v[210:213], v[8:11]
	v_mfma_f32_16x16x32_bf16 v[60:63], v[158:161], v[190:193], v[60:63]
	v_mfma_f32_16x16x32_bf16 v[56:59], v[166:169], v[190:193], v[56:59]
	v_mfma_f32_16x16x32_bf16 v[44:47], v[158:161], v[198:201], v[44:47]
	v_mfma_f32_16x16x32_bf16 v[40:43], v[166:169], v[198:201], v[40:43]
	v_mfma_f32_16x16x32_bf16 v[28:31], v[158:161], v[206:209], v[28:31]
	v_mfma_f32_16x16x32_bf16 v[24:27], v[166:169], v[206:209], v[24:27]
	v_mfma_f32_16x16x32_bf16 v[12:15], v[158:161], v[214:217], v[12:15]
	v_mfma_f32_16x16x32_bf16 v[8:11], v[166:169], v[214:217], v[8:11]
	s_setprio 0
	s_setprio 1
	v_mfma_f32_16x16x32_bf16 v[52:55], v[170:173], v[186:189], v[52:55]
	v_mfma_f32_16x16x32_bf16 v[48:51], v[178:181], v[186:189], v[48:51]
	v_mfma_f32_16x16x32_bf16 v[36:39], v[170:173], v[194:197], v[36:39]
	v_mfma_f32_16x16x32_bf16 v[32:35], v[178:181], v[194:197], v[32:35]
	v_mfma_f32_16x16x32_bf16 v[20:23], v[170:173], v[202:205], v[20:23]
	v_mfma_f32_16x16x32_bf16 v[16:19], v[178:181], v[202:205], v[16:19]
	v_mfma_f32_16x16x32_bf16 v[4:7], v[170:173], v[210:213], v[4:7]
	v_mfma_f32_16x16x32_bf16 v[0:3], v[178:181], v[210:213], v[0:3]
	v_mfma_f32_16x16x32_bf16 v[52:55], v[174:177], v[190:193], v[52:55]
	v_mfma_f32_16x16x32_bf16 v[48:51], v[182:185], v[190:193], v[48:51]
	v_mfma_f32_16x16x32_bf16 v[36:39], v[174:177], v[198:201], v[36:39]
	v_mfma_f32_16x16x32_bf16 v[32:35], v[182:185], v[198:201], v[32:35]
	v_mfma_f32_16x16x32_bf16 v[20:23], v[174:177], v[206:209], v[20:23]
	v_mfma_f32_16x16x32_bf16 v[16:19], v[182:185], v[206:209], v[16:19]
	v_mfma_f32_16x16x32_bf16 v[4:7], v[174:177], v[214:217], v[4:7]
	v_mfma_f32_16x16x32_bf16 v[0:3], v[182:185], v[214:217], v[0:3]
	s_barrier
	s_setprio 0
	s_add_i32 s71, s71, 2
	s_add_u32 s34, s34, 0x100
	s_addc_u32 s35, s35, 0
	s_add_u32 s69, s69, 0x100
	s_addc_u32 s70, s70, 0
	s_cmp_gt_u32 s71, 13
	s_cbranch_scc0 .LBB0_217
	s_and_b64 vcc, exec, s[14:15]
	s_cbranch_vccz .LBB0_220
	s_barrier

.LBB0_512:
	s_or_b64 exec, exec, s[14:15]
	v_cvt_f32_u32_e32 v4, v2
	s_waitcnt vmcnt(0)
	v_readfirstlane_b32 s4, v3
	v_sub_u32_e32 v3, 0, v2
	v_rcp_iflag_f32_e32 v4, v4
	v_add_u32_e32 v5, s4, v1
	v_mul_f32_e32 v4, 0x4f7ffffe, v4
	v_cvt_u32_f32_e32 v4, v4
	v_mul_lo_u32 v1, v3, v4
	v_mul_hi_u32 v1, v4, v1
	v_add_u32_e32 v1, v4, v1
	v_mul_hi_u32 v1, v5, v1
	v_mul_lo_u32 v3, v1, v2
	v_sub_u32_e32 v3, v5, v3
	v_add_u32_e32 v4, 1, v1
	v_cmp_ge_u32_e32 vcc, v3, v2
	s_nop 1
	v_cndmask_b32_e32 v1, v1, v4, vcc
	v_sub_u32_e32 v4, v3, v2
	v_cndmask_b32_e32 v3, v3, v4, vcc
	v_add_u32_e32 v4, 1, v1
	v_cmp_ge_u32_e32 vcc, v3, v2
	v_add_u32_e32 v3, 1, v5
	s_nop 0
	v_cndmask_b32_e32 v1, v1, v4, vcc
	v_mul_lo_u32 v4, v2, v1
	v_add_u32_e32 v2, v4, v2
	v_cmp_ne_u32_e32 vcc, v3, v2
	s_and_saveexec_b64 s[4:5], vcc
	s_xor_b64 s[12:13], exec, s[4:5]
	s_cbranch_execz .LBB0_526
	s_waitcnt lgkmcnt(0)
	v_mad_u32_u24 v3, v1, v0, v0
	v_mov_b32_e32 v0, 0x3000
	global_load_dword v0, v0, s[54:55] offset:1024 sc1
	s_add_u32 s16, s54, 0x3400
	s_addc_u32 s17, s55, 0
	s_waitcnt vmcnt(0)
	v_cmp_lt_u32_e32 vcc, v0, v3
	s_and_saveexec_b64 s[14:15], vcc
	s_cbranch_execz .LBB0_525
	s_mov_b32 s4, 1
	s_mov_b64 s[18:19], 0
	v_mov_b32_e32 v0, 0
	s_branch .LBB0_516

.LBB0_520:
	global_load_dword v2, v0, s[16:17] sc1
	s_add_i32 s4, s4, 1
	s_mov_b64 s[24:25], -1
	s_waitcnt vmcnt(0)
	v_cmp_ge_u32_e32 vcc, v2, v3
	s_orn2_b64 s[22:23], vcc, exec
	s_branch .LBB0_515

.LBB0_529:
	s_or_b64 exec, exec, s[14:15]
	v_cvt_f32_u32_e32 v3, v0
	s_waitcnt vmcnt(0)
	v_readfirstlane_b32 s4, v2
	s_add_u32 s14, s54, 0x3500
	s_addc_u32 s15, s55, 0
	v_rcp_iflag_f32_e32 v3, v3
	v_add_u32_e32 v1, s4, v1
	v_add_u32_e32 v4, 1, v1
	s_mov_b64 s[16:17], -1
	v_mul_f32_e32 v2, 0x4f7ffffe, v3
	v_cvt_u32_f32_e32 v2, v2
	v_sub_u32_e32 v3, 0, v0
	v_mul_lo_u32 v3, v3, v2
	v_mul_hi_u32 v3, v2, v3
	v_add_u32_e32 v2, v2, v3
	v_mul_hi_u32 v2, v1, v2
	v_mul_lo_u32 v3, v2, v0
	v_sub_u32_e32 v1, v1, v3
	v_add_u32_e32 v5, 1, v2
	v_cmp_ge_u32_e32 vcc, v1, v0
	v_sub_u32_e32 v3, v1, v0
	s_nop 0
	v_cndmask_b32_e32 v2, v2, v5, vcc
	v_cndmask_b32_e32 v1, v1, v3, vcc
	v_add_u32_e32 v3, 1, v2
	v_cmp_ge_u32_e32 vcc, v1, v0
	s_nop 1
	v_cndmask_b32_e32 v2, v2, v3, vcc
	v_mul_lo_u32 v1, v0, v2
	v_add_u32_e32 v0, v1, v0
	v_cmp_ne_u32_e32 vcc, v4, v0
	v_mov_b32_e32 v3, v0
	v_mov_b64_e32 v[0:1], s[14:15]
	s_and_saveexec_b64 s[12:13], vcc
	s_cbranch_execz .LBB0_541
	v_mov_b32_e32 v0, 0
	global_load_dword v1, v0, s[14:15] offset:-256 sc1
	s_mov_b64 s[20:21], 0
	s_waitcnt vmcnt(0)
	v_cmp_lt_u32_e32 vcc, v1, v3
	s_and_saveexec_b64 s[18:19], vcc
	s_cbranch_execz .LBB0_540
	s_add_u32 s16, s54, 0x200
	s_addc_u32 s17, s55, 0
	s_mov_b32 s4, 1
	s_branch .LBB0_533

.LBB0_537:
	global_load_dword v1, v0, s[14:15] offset:-256 sc1
	s_add_i32 s4, s4, 1
	s_mov_b64 s[24:25], -1
	s_waitcnt vmcnt(0)
	v_cmp_ge_u32_e32 vcc, v1, v3
	s_orn2_b64 s[28:29], vcc, exec
	s_branch .LBB0_532

.Lph555_w:
	s_nop 0
	s_nop 0
	s_nop 0
	s_waitcnt vmcnt(8)
	s_waitcnt lgkmcnt(0)
	s_setprio 1
	s_barrier
	v_mfma_f32_16x16x32_bf16 v[116:119], v[154:157], v[186:189], v[116:119]
	v_mfma_f32_16x16x32_bf16 v[112:115], v[162:165], v[186:189], v[112:115]
	v_mfma_f32_16x16x32_bf16 v[108:111], v[154:157], v[194:197], v[108:111]
	v_mfma_f32_16x16x32_bf16 v[100:103], v[162:165], v[194:197], v[100:103]
	v_mfma_f32_16x16x32_bf16 v[92:95], v[154:157], v[202:205], v[92:95]
	v_mfma_f32_16x16x32_bf16 v[84:87], v[162:165], v[202:205], v[84:87]
	v_mfma_f32_16x16x32_bf16 v[76:79], v[154:157], v[210:213], v[76:79]
	v_mfma_f32_16x16x32_bf16 v[68:71], v[162:165], v[210:213], v[68:71]
	v_mfma_f32_16x16x32_bf16 v[116:119], v[158:161], v[190:193], v[116:119]
	v_mfma_f32_16x16x32_bf16 v[112:115], v[166:169], v[190:193], v[112:115]
	v_mfma_f32_16x16x32_bf16 v[108:111], v[158:161], v[198:201], v[108:111]
	v_mfma_f32_16x16x32_bf16 v[100:103], v[166:169], v[198:201], v[100:103]
	v_mfma_f32_16x16x32_bf16 v[92:95], v[158:161], v[206:209], v[92:95]
	v_mfma_f32_16x16x32_bf16 v[84:87], v[166:169], v[206:209], v[84:87]
	v_mfma_f32_16x16x32_bf16 v[76:79], v[158:161], v[214:217], v[76:79]
	v_mfma_f32_16x16x32_bf16 v[68:71], v[166:169], v[214:217], v[68:71]
	s_setprio 0
	s_setprio 1
	v_mfma_f32_16x16x32_bf16 v[124:127], v[170:173], v[186:189], v[124:127]
	v_mfma_f32_16x16x32_bf16 v[120:123], v[178:181], v[186:189], v[120:123]
	v_mfma_f32_16x16x32_bf16 v[104:107], v[170:173], v[194:197], v[104:107]
	v_mfma_f32_16x16x32_bf16 v[96:99], v[178:181], v[194:197], v[96:99]
	v_mfma_f32_16x16x32_bf16 v[88:91], v[170:173], v[202:205], v[88:91]
	v_mfma_f32_16x16x32_bf16 v[80:83], v[178:181], v[202:205], v[80:83]
	v_mfma_f32_16x16x32_bf16 v[72:75], v[170:173], v[210:213], v[72:75]
	v_mfma_f32_16x16x32_bf16 v[64:67], v[178:181], v[210:213], v[64:67]
	v_mfma_f32_16x16x32_bf16 v[124:127], v[174:177], v[190:193], v[124:127]
	v_mfma_f32_16x16x32_bf16 v[120:123], v[182:185], v[190:193], v[120:123]
	v_mfma_f32_16x16x32_bf16 v[104:107], v[174:177], v[198:201], v[104:107]
	v_mfma_f32_16x16x32_bf16 v[96:99], v[182:185], v[198:201], v[96:99]
	v_mfma_f32_16x16x32_bf16 v[88:91], v[174:177], v[206:209], v[88:91]
	v_mfma_f32_16x16x32_bf16 v[80:83], v[182:185], v[206:209], v[80:83]
	v_mfma_f32_16x16x32_bf16 v[72:75], v[174:177], v[214:217], v[72:75]
	v_mfma_f32_16x16x32_bf16 v[64:67], v[182:185], v[214:217], v[64:67]
	s_barrier
	s_setprio 0
	s_add_i32 s64, s48, s36
	v_lshl_add_u64 v[144:145], s[30:31], 0, v[132:133]
	s_mov_b32 m0, s64
	s_nop 0
	global_load_lds_dwordx4 v[144:145], off
	s_add_i32 m0, s64, 0x2000
	s_add_u32 s64, s30, 0x40000
	v_lshl_add_u64 v[218:219], s[30:31], 0, v[128:129]
	s_addc_u32 s65, s31, 0
	s_add_i32 s68, s49, s36
	global_load_lds_dwordx4 v[218:219], off
	v_lshl_add_u64 v[220:221], s[64:65], 0, v[132:133]
	s_mov_b32 m0, s68
	v_lshl_add_u64 v[222:223], s[34:35], 0, v[130:131]
	global_load_lds_dwordx4 v[220:221], off
	v_lshl_add_u64 v[220:221], s[64:65], 0, v[128:129]
	s_add_i32 m0, s68, 0x2000
	s_nop 0
	global_load_lds_dwordx4 v[220:221], off
	v_lshl_add_u64 v[220:221], s[34:35], 0, v[134:135]
	s_mov_b32 m0, s25
	s_nop 0
	global_load_lds_dwordx4 v[220:221], off
	s_mov_b32 m0, s27
	s_nop 0
	global_load_lds_dwordx4 v[222:223], off
	ds_read_b128 v[186:189], v151 offset:16384
	ds_read_b128 v[190:193], v151 offset:17408
	ds_read_b128 v[194:197], v151 offset:18432
	ds_read_b128 v[198:201], v151 offset:19456
	ds_read_b128 v[202:205], v151 offset:20480
	ds_read_b128 v[206:209], v151 offset:21504
	ds_read_b128 v[210:213], v151 offset:22528
	ds_read_b128 v[214:217], v151 offset:23552
	s_nop 0
	s_waitcnt vmcnt(8)
	s_waitcnt lgkmcnt(0)
	s_setprio 1
	s_barrier
	v_mfma_f32_16x16x32_bf16 v[60:63], v[154:157], v[186:189], v[60:63]
	v_mfma_f32_16x16x32_bf16 v[52:55], v[162:165], v[186:189], v[52:55]
	v_mfma_f32_16x16x32_bf16 v[44:47], v[154:157], v[194:197], v[44:47]
	v_mfma_f32_16x16x32_bf16 v[36:39], v[162:165], v[194:197], v[36:39]
	v_mfma_f32_16x16x32_bf16 v[28:31], v[154:157], v[202:205], v[28:31]
	v_mfma_f32_16x16x32_bf16 v[20:23], v[162:165], v[202:205], v[20:23]
	v_mfma_f32_16x16x32_bf16 v[12:15], v[154:157], v[210:213], v[12:15]
	v_mfma_f32_16x16x32_bf16 v[4:7], v[162:165], v[210:213], v[4:7]
	v_mfma_f32_16x16x32_bf16 v[60:63], v[158:161], v[190:193], v[60:63]
	v_mfma_f32_16x16x32_bf16 v[52:55], v[166:169], v[190:193], v[52:55]
	v_mfma_f32_16x16x32_bf16 v[44:47], v[158:161], v[198:201], v[44:47]
	v_mfma_f32_16x16x32_bf16 v[36:39], v[166:169], v[198:201], v[36:39]
	v_mfma_f32_16x16x32_bf16 v[28:31], v[158:161], v[206:209], v[28:31]
	v_mfma_f32_16x16x32_bf16 v[20:23], v[166:169], v[206:209], v[20:23]
	v_mfma_f32_16x16x32_bf16 v[12:15], v[158:161], v[214:217], v[12:15]
	v_mfma_f32_16x16x32_bf16 v[4:7], v[166:169], v[214:217], v[4:7]
	s_setprio 0
	s_setprio 1
	v_mfma_f32_16x16x32_bf16 v[56:59], v[170:173], v[186:189], v[56:59]
	v_mfma_f32_16x16x32_bf16 v[48:51], v[178:181], v[186:189], v[48:51]
	v_mfma_f32_16x16x32_bf16 v[40:43], v[170:173], v[194:197], v[40:43]
	v_mfma_f32_16x16x32_bf16 v[32:35], v[178:181], v[194:197], v[32:35]
	v_mfma_f32_16x16x32_bf16 v[24:27], v[170:173], v[202:205], v[24:27]
	v_mfma_f32_16x16x32_bf16 v[16:19], v[178:181], v[202:205], v[16:19]
	v_mfma_f32_16x16x32_bf16 v[8:11], v[170:173], v[210:213], v[8:11]
	v_mfma_f32_16x16x32_bf16 v[0:3], v[178:181], v[210:213], v[0:3]
	v_mfma_f32_16x16x32_bf16 v[56:59], v[174:177], v[190:193], v[56:59]
	v_mfma_f32_16x16x32_bf16 v[48:51], v[182:185], v[190:193], v[48:51]
	v_mfma_f32_16x16x32_bf16 v[40:43], v[174:177], v[198:201], v[40:43]
	v_mfma_f32_16x16x32_bf16 v[32:35], v[182:185], v[198:201], v[32:35]
	v_mfma_f32_16x16x32_bf16 v[24:27], v[174:177], v[206:209], v[24:27]
	v_mfma_f32_16x16x32_bf16 v[16:19], v[182:185], v[206:209], v[16:19]
	v_mfma_f32_16x16x32_bf16 v[8:11], v[174:177], v[214:217], v[8:11]
	v_mfma_f32_16x16x32_bf16 v[0:3], v[182:185], v[214:217], v[0:3]
	s_barrier
	s_setprio 0
	s_add_i32 s64, 0, 0x18000
	s_add_i32 s65, 0, 0x1c000
	s_add_u32 s34, s34, 0x40000
	s_addc_u32 s35, s35, 0
	s_mov_b32 m0, s39
	v_lshl_add_u64 v[224:225], s[34:35], 0, v[134:135]
	global_load_lds_dwordx4 v[224:225], off
	v_lshl_add_u64 v[224:225], s[34:35], 0, v[130:131]
	s_mov_b32 m0, s40
	s_nop 0
	global_load_lds_dwordx4 v[224:225], off
	v_add_u32_e32 v153, s64, v147
	ds_read_b128 v[154:157], v153
	ds_read_b128 v[158:161], v153 offset:1024
	ds_read_b128 v[162:165], v153 offset:2048
	ds_read_b128 v[166:169], v153 offset:3072
	v_add_u32_e32 v153, s65, v147
	ds_read_b128 v[170:173], v153
	ds_read_b128 v[174:177], v153 offset:1024
	ds_read_b128 v[178:181], v153 offset:2048
	ds_read_b128 v[182:185], v153 offset:3072
	ds_read_b128 v[186:189], v151 offset:32768
	ds_read_b128 v[190:193], v151 offset:33792
	ds_read_b128 v[194:197], v151 offset:34816
	ds_read_b128 v[198:201], v151 offset:35840
	ds_read_b128 v[202:205], v151 offset:36864
	ds_read_b128 v[206:209], v151 offset:37888
	ds_read_b128 v[210:213], v151 offset:38912
	ds_read_b128 v[214:217], v151 offset:39936
	s_waitcnt vmcnt(8)
	s_waitcnt lgkmcnt(0)
	s_setprio 1
	s_barrier
	v_mfma_f32_16x16x32_bf16 v[116:119], v[154:157], v[186:189], v[116:119]
	v_mfma_f32_16x16x32_bf16 v[112:115], v[162:165], v[186:189], v[112:115]
	v_mfma_f32_16x16x32_bf16 v[108:111], v[154:157], v[194:197], v[108:111]
	v_mfma_f32_16x16x32_bf16 v[100:103], v[162:165], v[194:197], v[100:103]
	v_mfma_f32_16x16x32_bf16 v[92:95], v[154:157], v[202:205], v[92:95]
	v_mfma_f32_16x16x32_bf16 v[84:87], v[162:165], v[202:205], v[84:87]
	v_mfma_f32_16x16x32_bf16 v[76:79], v[154:157], v[210:213], v[76:79]
	v_mfma_f32_16x16x32_bf16 v[68:71], v[162:165], v[210:213], v[68:71]
	v_mfma_f32_16x16x32_bf16 v[116:119], v[158:161], v[190:193], v[116:119]
	v_mfma_f32_16x16x32_bf16 v[112:115], v[166:169], v[190:193], v[112:115]
	v_mfma_f32_16x16x32_bf16 v[108:111], v[158:161], v[198:201], v[108:111]
	v_mfma_f32_16x16x32_bf16 v[100:103], v[166:169], v[198:201], v[100:103]
	v_mfma_f32_16x16x32_bf16 v[92:95], v[158:161], v[206:209], v[92:95]
	v_mfma_f32_16x16x32_bf16 v[84:87], v[166:169], v[206:209], v[84:87]
	v_mfma_f32_16x16x32_bf16 v[76:79], v[158:161], v[214:217], v[76:79]
	v_mfma_f32_16x16x32_bf16 v[68:71], v[166:169], v[214:217], v[68:71]
	s_setprio 0
	s_setprio 1
	v_mfma_f32_16x16x32_bf16 v[124:127], v[170:173], v[186:189], v[124:127]
	v_mfma_f32_16x16x32_bf16 v[120:123], v[178:181], v[186:189], v[120:123]
	v_mfma_f32_16x16x32_bf16 v[104:107], v[170:173], v[194:197], v[104:107]
	v_mfma_f32_16x16x32_bf16 v[96:99], v[178:181], v[194:197], v[96:99]
	v_mfma_f32_16x16x32_bf16 v[88:91], v[170:173], v[202:205], v[88:91]
	v_mfma_f32_16x16x32_bf16 v[80:83], v[178:181], v[202:205], v[80:83]
	v_mfma_f32_16x16x32_bf16 v[72:75], v[170:173], v[210:213], v[72:75]
	v_mfma_f32_16x16x32_bf16 v[64:67], v[178:181], v[210:213], v[64:67]
	v_mfma_f32_16x16x32_bf16 v[124:127], v[174:177], v[190:193], v[124:127]
	v_mfma_f32_16x16x32_bf16 v[120:123], v[182:185], v[190:193], v[120:123]
	v_mfma_f32_16x16x32_bf16 v[104:107], v[174:177], v[198:201], v[104:107]
	v_mfma_f32_16x16x32_bf16 v[96:99], v[182:185], v[198:201], v[96:99]
	v_mfma_f32_16x16x32_bf16 v[88:91], v[174:177], v[206:209], v[88:91]
	v_mfma_f32_16x16x32_bf16 v[80:83], v[182:185], v[206:209], v[80:83]
	v_mfma_f32_16x16x32_bf16 v[72:75], v[174:177], v[214:217], v[72:75]
	v_mfma_f32_16x16x32_bf16 v[64:67], v[182:185], v[214:217], v[64:67]
	s_barrier
	s_setprio 0
	s_add_i32 s34, s64, s36
	v_lshl_add_u64 v[144:145], v[144:145], 0, s[12:13]
	s_mov_b32 m0, s34
	s_nop 0
	global_load_lds_dwordx4 v[144:145], off
	s_add_i32 m0, s34, 0x2000
	s_add_u32 s30, s30, 0x40080
	v_lshl_add_u64 v[144:145], v[218:219], 0, s[12:13]
	s_addc_u32 s31, s31, 0
	s_add_i32 s34, s65, s36
	global_load_lds_dwordx4 v[144:145], off
	v_lshl_add_u64 v[144:145], s[30:31], 0, v[132:133]
	s_mov_b32 m0, s34
	s_nop 0
	global_load_lds_dwordx4 v[144:145], off
	v_lshl_add_u64 v[144:145], s[30:31], 0, v[128:129]
	s_add_i32 m0, s34, 0x2000
	s_nop 0
	global_load_lds_dwordx4 v[144:145], off
	v_lshl_add_u64 v[144:145], v[220:221], 0, s[12:13]
	s_mov_b32 m0, s42
	s_nop 0
	global_load_lds_dwordx4 v[144:145], off
	v_lshl_add_u64 v[144:145], v[222:223], 0, s[12:13]
	s_mov_b32 m0, s43
	s_nop 0
	global_load_lds_dwordx4 v[144:145], off
	ds_read_b128 v[186:189], v151 offset:49152
	ds_read_b128 v[190:193], v151 offset:50176
	ds_read_b128 v[194:197], v151 offset:51200
	ds_read_b128 v[198:201], v151 offset:52224
	ds_read_b128 v[202:205], v151 offset:53248
	ds_read_b128 v[206:209], v151 offset:54272
	ds_read_b128 v[210:213], v151 offset:55296
	ds_read_b128 v[214:217], v151 offset:56320
	s_waitcnt vmcnt(8)
	s_waitcnt lgkmcnt(0)
	s_setprio 1
	s_barrier
	v_mfma_f32_16x16x32_bf16 v[60:63], v[154:157], v[186:189], v[60:63]
	v_mfma_f32_16x16x32_bf16 v[52:55], v[162:165], v[186:189], v[52:55]
	v_mfma_f32_16x16x32_bf16 v[44:47], v[154:157], v[194:197], v[44:47]
	v_mfma_f32_16x16x32_bf16 v[36:39], v[162:165], v[194:197], v[36:39]
	v_mfma_f32_16x16x32_bf16 v[28:31], v[154:157], v[202:205], v[28:31]
	v_mfma_f32_16x16x32_bf16 v[20:23], v[162:165], v[202:205], v[20:23]
	v_mfma_f32_16x16x32_bf16 v[12:15], v[154:157], v[210:213], v[12:15]
	v_mfma_f32_16x16x32_bf16 v[4:7], v[162:165], v[210:213], v[4:7]
	v_mfma_f32_16x16x32_bf16 v[60:63], v[158:161], v[190:193], v[60:63]
	v_mfma_f32_16x16x32_bf16 v[52:55], v[166:169], v[190:193], v[52:55]
	v_mfma_f32_16x16x32_bf16 v[44:47], v[158:161], v[198:201], v[44:47]
	v_mfma_f32_16x16x32_bf16 v[36:39], v[166:169], v[198:201], v[36:39]
	v_mfma_f32_16x16x32_bf16 v[28:31], v[158:161], v[206:209], v[28:31]
	v_mfma_f32_16x16x32_bf16 v[20:23], v[166:169], v[206:209], v[20:23]
	v_mfma_f32_16x16x32_bf16 v[12:15], v[158:161], v[214:217], v[12:15]
	v_mfma_f32_16x16x32_bf16 v[4:7], v[166:169], v[214:217], v[4:7]
	s_setprio 0
	s_setprio 1
	v_mfma_f32_16x16x32_bf16 v[56:59], v[170:173], v[186:189], v[56:59]
	v_mfma_f32_16x16x32_bf16 v[48:51], v[178:181], v[186:189], v[48:51]
	v_mfma_f32_16x16x32_bf16 v[40:43], v[170:173], v[194:197], v[40:43]
	v_mfma_f32_16x16x32_bf16 v[32:35], v[178:181], v[194:197], v[32:35]
	v_mfma_f32_16x16x32_bf16 v[24:27], v[170:173], v[202:205], v[24:27]
	v_mfma_f32_16x16x32_bf16 v[16:19], v[178:181], v[202:205], v[16:19]
	v_mfma_f32_16x16x32_bf16 v[8:11], v[170:173], v[210:213], v[8:11]
	v_mfma_f32_16x16x32_bf16 v[0:3], v[178:181], v[210:213], v[0:3]
	v_mfma_f32_16x16x32_bf16 v[56:59], v[174:177], v[190:193], v[56:59]
	v_mfma_f32_16x16x32_bf16 v[48:51], v[182:185], v[190:193], v[48:51]
	v_mfma_f32_16x16x32_bf16 v[40:43], v[174:177], v[198:201], v[40:43]
	v_mfma_f32_16x16x32_bf16 v[32:35], v[182:185], v[198:201], v[32:35]
	v_mfma_f32_16x16x32_bf16 v[24:27], v[174:177], v[206:209], v[24:27]
	v_mfma_f32_16x16x32_bf16 v[16:19], v[182:185], v[206:209], v[16:19]
	v_mfma_f32_16x16x32_bf16 v[8:11], v[174:177], v[214:217], v[8:11]
	v_mfma_f32_16x16x32_bf16 v[0:3], v[182:185], v[214:217], v[0:3]
	s_barrier
	s_setprio 0
	s_add_i32 s63, s63, 2
	s_add_u32 s28, s28, 0x100
	s_addc_u32 s29, s29, 0
	s_add_u32 s61, s61, 0x100
	s_addc_u32 s62, s62, 0
	s_cmp_gt_u32 s63, 13
	s_cbranch_scc0 .LBB0_555
	s_and_b64 vcc, exec, s[14:15]
	s_cbranch_vccz .LBB0_558
	s_barrier

.LBB0_580:
	s_or_b64 exec, exec, s[12:13]
	v_cvt_f32_u32_e32 v4, v2
	s_waitcnt vmcnt(0)
	v_readfirstlane_b32 s4, v3
	v_sub_u32_e32 v3, 0, v2
	v_rcp_iflag_f32_e32 v4, v4
	v_add_u32_e32 v5, s4, v1
	v_mul_f32_e32 v4, 0x4f7ffffe, v4
	v_cvt_u32_f32_e32 v4, v4
	v_mul_lo_u32 v1, v3, v4
	v_mul_hi_u32 v1, v4, v1
	v_add_u32_e32 v1, v4, v1
	v_mul_hi_u32 v1, v5, v1
	v_mul_lo_u32 v3, v1, v2
	v_sub_u32_e32 v3, v5, v3
	v_add_u32_e32 v4, 1, v1
	v_cmp_ge_u32_e32 vcc, v3, v2
	s_nop 1
	v_cndmask_b32_e32 v1, v1, v4, vcc
	v_sub_u32_e32 v4, v3, v2
	v_cndmask_b32_e32 v3, v3, v4, vcc
	v_add_u32_e32 v4, 1, v1
	v_cmp_ge_u32_e32 vcc, v3, v2
	v_add_u32_e32 v3, 1, v5
	s_nop 0
	v_cndmask_b32_e32 v1, v1, v4, vcc
	v_mul_lo_u32 v4, v2, v1
	v_add_u32_e32 v2, v4, v2
	v_cmp_ne_u32_e32 vcc, v3, v2
	s_and_saveexec_b64 s[4:5], vcc
	s_xor_b64 s[10:11], exec, s[4:5]
	s_cbranch_execz .LBB0_594
	s_waitcnt lgkmcnt(0)
	v_mad_u32_u24 v3, v1, v0, v0
	v_mov_b32_e32 v0, 0x3000
	global_load_dword v0, v0, s[54:55] offset:1024 sc1
	s_add_u32 s14, s54, 0x3400
	s_addc_u32 s15, s55, 0
	s_waitcnt vmcnt(0)
	v_cmp_lt_u32_e32 vcc, v0, v3
	s_and_saveexec_b64 s[12:13], vcc
	s_cbranch_execz .LBB0_593
	s_mov_b32 s4, 1
	s_mov_b64 s[16:17], 0
	v_mov_b32_e32 v0, 0
	s_branch .LBB0_584

.LBB0_588:
	global_load_dword v2, v0, s[14:15] sc1
	s_add_i32 s4, s4, 1
	s_mov_b64 s[22:23], -1
	s_waitcnt vmcnt(0)
	v_cmp_ge_u32_e32 vcc, v2, v3
	s_orn2_b64 s[20:21], vcc, exec
	s_branch .LBB0_583

.LBB0_597:
	s_or_b64 exec, exec, s[12:13]
	v_cvt_f32_u32_e32 v3, v0
	s_waitcnt vmcnt(0)
	v_readfirstlane_b32 s4, v2
	s_add_u32 s12, s54, 0x3500
	s_addc_u32 s13, s55, 0
	v_rcp_iflag_f32_e32 v3, v3
	v_add_u32_e32 v1, s4, v1
	v_add_u32_e32 v4, 1, v1
	s_mov_b64 s[14:15], -1
	v_mul_f32_e32 v2, 0x4f7ffffe, v3
	v_cvt_u32_f32_e32 v2, v2
	v_sub_u32_e32 v3, 0, v0
	v_mul_lo_u32 v3, v3, v2
	v_mul_hi_u32 v3, v2, v3
	v_add_u32_e32 v2, v2, v3
	v_mul_hi_u32 v2, v1, v2
	v_mul_lo_u32 v3, v2, v0
	v_sub_u32_e32 v1, v1, v3
	v_add_u32_e32 v5, 1, v2
	v_cmp_ge_u32_e32 vcc, v1, v0
	v_sub_u32_e32 v3, v1, v0
	s_nop 0
	v_cndmask_b32_e32 v2, v2, v5, vcc
	v_cndmask_b32_e32 v1, v1, v3, vcc
	v_add_u32_e32 v3, 1, v2
	v_cmp_ge_u32_e32 vcc, v1, v0
	s_nop 1
	v_cndmask_b32_e32 v2, v2, v3, vcc
	v_mul_lo_u32 v1, v0, v2
	v_add_u32_e32 v0, v1, v0
	v_cmp_ne_u32_e32 vcc, v4, v0
	v_mov_b32_e32 v3, v0
	v_mov_b64_e32 v[0:1], s[12:13]
	s_and_saveexec_b64 s[10:11], vcc
	s_cbranch_execz .LBB0_609
	v_mov_b32_e32 v0, 0
	global_load_dword v1, v0, s[12:13] offset:-256 sc1
	s_mov_b64 s[18:19], 0
	s_waitcnt vmcnt(0)
	v_cmp_lt_u32_e32 vcc, v1, v3
	s_and_saveexec_b64 s[16:17], vcc
	s_cbranch_execz .LBB0_608
	s_add_u32 s14, s54, 0x200
	s_addc_u32 s15, s55, 0
	s_mov_b32 s4, 1
	s_branch .LBB0_601

.LBB0_605:
	global_load_dword v1, v0, s[12:13] offset:-256 sc1
	s_add_i32 s4, s4, 1
	s_mov_b64 s[22:23], -1
	s_waitcnt vmcnt(0)
	v_cmp_ge_u32_e32 vcc, v1, v3
	s_orn2_b64 s[26:27], vcc, exec
	s_branch .LBB0_600

.Lph637_w:
	s_nop 0
	s_nop 0
	s_nop 0
	s_waitcnt vmcnt(8)
	s_waitcnt lgkmcnt(0)
	s_setprio 1
	s_barrier
	v_mfma_f32_16x16x32_bf16 v[144:147], v[120:123], v[160:163], v[144:147]
	v_mfma_f32_16x16x32_bf16 v[136:139], v[128:131], v[160:163], v[136:139]
	v_mfma_f32_16x16x32_bf16 v[108:111], v[120:123], v[168:171], v[108:111]
	v_mfma_f32_16x16x32_bf16 v[104:107], v[128:131], v[168:171], v[104:107]
	v_mfma_f32_16x16x32_bf16 v[92:95], v[120:123], v[176:179], v[92:95]
	v_mfma_f32_16x16x32_bf16 v[88:91], v[128:131], v[176:179], v[88:91]
	v_mfma_f32_16x16x32_bf16 v[76:79], v[120:123], v[184:187], v[76:79]
	v_mfma_f32_16x16x32_bf16 v[72:75], v[128:131], v[184:187], v[72:75]
	v_mfma_f32_16x16x32_bf16 v[144:147], v[124:127], v[164:167], v[144:147]
	v_mfma_f32_16x16x32_bf16 v[136:139], v[132:135], v[164:167], v[136:139]
	v_mfma_f32_16x16x32_bf16 v[108:111], v[124:127], v[172:175], v[108:111]
	v_mfma_f32_16x16x32_bf16 v[104:107], v[132:135], v[172:175], v[104:107]
	v_mfma_f32_16x16x32_bf16 v[92:95], v[124:127], v[180:183], v[92:95]
	v_mfma_f32_16x16x32_bf16 v[88:91], v[132:135], v[180:183], v[88:91]
	v_mfma_f32_16x16x32_bf16 v[76:79], v[124:127], v[188:191], v[76:79]
	v_mfma_f32_16x16x32_bf16 v[72:75], v[132:135], v[188:191], v[72:75]
	s_setprio 0
	s_setprio 1
	v_mfma_f32_16x16x32_bf16 v[116:119], v[140:143], v[160:163], v[116:119]
	v_mfma_f32_16x16x32_bf16 v[112:115], v[152:155], v[160:163], v[112:115]
	v_mfma_f32_16x16x32_bf16 v[100:103], v[140:143], v[168:171], v[100:103]
	v_mfma_f32_16x16x32_bf16 v[96:99], v[152:155], v[168:171], v[96:99]
	v_mfma_f32_16x16x32_bf16 v[84:87], v[140:143], v[176:179], v[84:87]
	v_mfma_f32_16x16x32_bf16 v[80:83], v[152:155], v[176:179], v[80:83]
	v_mfma_f32_16x16x32_bf16 v[68:71], v[140:143], v[184:187], v[68:71]
	v_mfma_f32_16x16x32_bf16 v[64:67], v[152:155], v[184:187], v[64:67]
	v_mfma_f32_16x16x32_bf16 v[116:119], v[148:151], v[164:167], v[116:119]
	v_mfma_f32_16x16x32_bf16 v[112:115], v[156:159], v[164:167], v[112:115]
	v_mfma_f32_16x16x32_bf16 v[100:103], v[148:151], v[172:175], v[100:103]
	v_mfma_f32_16x16x32_bf16 v[96:99], v[156:159], v[172:175], v[96:99]
	v_mfma_f32_16x16x32_bf16 v[84:87], v[148:151], v[180:183], v[84:87]
	v_mfma_f32_16x16x32_bf16 v[80:83], v[156:159], v[180:183], v[80:83]
	v_mfma_f32_16x16x32_bf16 v[68:71], v[148:151], v[188:191], v[68:71]
	v_mfma_f32_16x16x32_bf16 v[64:67], v[156:159], v[188:191], v[64:67]
	s_barrier
	s_setprio 0
	s_add_i32 s20, s43, s28
	v_lshl_add_u64 v[206:207], s[24:25], 0, v[194:195]
	s_mov_b32 m0, s20
	s_nop 0
	global_load_lds_dwordx4 v[206:207], off
	s_add_i32 m0, s20, 0x2000
	s_add_u32 s20, s24, 0xb0000
	v_lshl_add_u64 v[208:209], s[24:25], 0, v[198:199]
	s_addc_u32 s21, s25, 0
	s_add_i32 s62, s46, s28
	global_load_lds_dwordx4 v[208:209], off
	v_lshl_add_u64 v[210:211], s[20:21], 0, v[194:195]
	s_mov_b32 m0, s62
	v_lshl_add_u64 v[212:213], s[26:27], 0, v[196:197]
	global_load_lds_dwordx4 v[210:211], off
	v_lshl_add_u64 v[210:211], s[20:21], 0, v[198:199]
	s_add_i32 m0, s62, 0x2000
	s_nop 0
	global_load_lds_dwordx4 v[210:211], off
	v_lshl_add_u64 v[210:211], s[26:27], 0, v[192:193]
	s_mov_b32 m0, s29
	s_nop 0
	global_load_lds_dwordx4 v[210:211], off
	s_mov_b32 m0, s30
	s_nop 0
	global_load_lds_dwordx4 v[212:213], off
	ds_read_b128 v[160:163], v249 offset:16384
	ds_read_b128 v[164:167], v249 offset:17408
	ds_read_b128 v[168:171], v249 offset:18432
	ds_read_b128 v[172:175], v249 offset:19456
	ds_read_b128 v[176:179], v249 offset:20480
	ds_read_b128 v[180:183], v249 offset:21504
	ds_read_b128 v[184:187], v249 offset:22528
	ds_read_b128 v[188:191], v249 offset:23552
	s_nop 0
	s_waitcnt vmcnt(8)
	s_waitcnt lgkmcnt(0)
	s_setprio 1
	s_barrier
	v_mfma_f32_16x16x32_bf16 v[60:63], v[120:123], v[160:163], v[60:63]
	v_mfma_f32_16x16x32_bf16 v[56:59], v[128:131], v[160:163], v[56:59]
	v_mfma_f32_16x16x32_bf16 v[44:47], v[120:123], v[168:171], v[44:47]
	v_mfma_f32_16x16x32_bf16 v[40:43], v[128:131], v[168:171], v[40:43]
	v_mfma_f32_16x16x32_bf16 v[28:31], v[120:123], v[176:179], v[28:31]
	v_mfma_f32_16x16x32_bf16 v[24:27], v[128:131], v[176:179], v[24:27]
	v_mfma_f32_16x16x32_bf16 v[12:15], v[120:123], v[184:187], v[12:15]
	v_mfma_f32_16x16x32_bf16 v[8:11], v[128:131], v[184:187], v[8:11]
	v_mfma_f32_16x16x32_bf16 v[60:63], v[124:127], v[164:167], v[60:63]
	v_mfma_f32_16x16x32_bf16 v[56:59], v[132:135], v[164:167], v[56:59]
	v_mfma_f32_16x16x32_bf16 v[44:47], v[124:127], v[172:175], v[44:47]
	v_mfma_f32_16x16x32_bf16 v[40:43], v[132:135], v[172:175], v[40:43]
	v_mfma_f32_16x16x32_bf16 v[28:31], v[124:127], v[180:183], v[28:31]
	v_mfma_f32_16x16x32_bf16 v[24:27], v[132:135], v[180:183], v[24:27]
	v_mfma_f32_16x16x32_bf16 v[12:15], v[124:127], v[188:191], v[12:15]
	v_mfma_f32_16x16x32_bf16 v[8:11], v[132:135], v[188:191], v[8:11]
	s_setprio 0
	s_setprio 1
	v_mfma_f32_16x16x32_bf16 v[52:55], v[140:143], v[160:163], v[52:55]
	v_mfma_f32_16x16x32_bf16 v[48:51], v[152:155], v[160:163], v[48:51]
	v_mfma_f32_16x16x32_bf16 v[36:39], v[140:143], v[168:171], v[36:39]
	v_mfma_f32_16x16x32_bf16 v[32:35], v[152:155], v[168:171], v[32:35]
	v_mfma_f32_16x16x32_bf16 v[20:23], v[140:143], v[176:179], v[20:23]
	v_mfma_f32_16x16x32_bf16 v[16:19], v[152:155], v[176:179], v[16:19]
	v_mfma_f32_16x16x32_bf16 v[4:7], v[140:143], v[184:187], v[4:7]
	v_mfma_f32_16x16x32_bf16 v[0:3], v[152:155], v[184:187], v[0:3]
	v_mfma_f32_16x16x32_bf16 v[52:55], v[148:151], v[164:167], v[52:55]
	v_mfma_f32_16x16x32_bf16 v[48:51], v[156:159], v[164:167], v[48:51]
	v_mfma_f32_16x16x32_bf16 v[36:39], v[148:151], v[172:175], v[36:39]
	v_mfma_f32_16x16x32_bf16 v[32:35], v[156:159], v[172:175], v[32:35]
	v_mfma_f32_16x16x32_bf16 v[20:23], v[148:151], v[180:183], v[20:23]
	v_mfma_f32_16x16x32_bf16 v[16:19], v[156:159], v[180:183], v[16:19]
	v_mfma_f32_16x16x32_bf16 v[4:7], v[148:151], v[188:191], v[4:7]
	v_mfma_f32_16x16x32_bf16 v[0:3], v[156:159], v[188:191], v[0:3]
	s_barrier
	s_setprio 0
	s_add_i32 s62, 0, 0x18000
	s_add_i32 s63, 0, 0x1c000
	s_add_u32 s20, s26, 0xb0000
	s_addc_u32 s21, s27, 0
	s_mov_b32 m0, s31
	v_lshl_add_u64 v[214:215], s[20:21], 0, v[192:193]
	global_load_lds_dwordx4 v[214:215], off
	v_lshl_add_u64 v[214:215], s[20:21], 0, v[196:197]
	s_mov_b32 m0, s34
	s_nop 0
	global_load_lds_dwordx4 v[214:215], off
	v_add_u32_e32 v132, s62, v246
	v_add_u32_e32 v156, s63, v246
	ds_read_b128 v[120:123], v132
	ds_read_b128 v[124:127], v132 offset:1024
	ds_read_b128 v[128:131], v132 offset:2048
	ds_read_b128 v[132:135], v132 offset:3072
	ds_read_b128 v[140:143], v156
	ds_read_b128 v[148:151], v156 offset:1024
	ds_read_b128 v[152:155], v156 offset:2048
	ds_read_b128 v[156:159], v156 offset:3072
	ds_read_b128 v[160:163], v249 offset:32768
	ds_read_b128 v[164:167], v249 offset:33792
	ds_read_b128 v[168:171], v249 offset:34816
	ds_read_b128 v[172:175], v249 offset:35840
	ds_read_b128 v[176:179], v249 offset:36864
	ds_read_b128 v[180:183], v249 offset:37888
	ds_read_b128 v[184:187], v249 offset:38912
	ds_read_b128 v[188:191], v249 offset:39936
	s_waitcnt vmcnt(8)
	s_waitcnt lgkmcnt(0)
	s_setprio 1
	s_barrier
	v_mfma_f32_16x16x32_bf16 v[144:147], v[120:123], v[160:163], v[144:147]
	v_mfma_f32_16x16x32_bf16 v[136:139], v[128:131], v[160:163], v[136:139]
	v_mfma_f32_16x16x32_bf16 v[108:111], v[120:123], v[168:171], v[108:111]
	v_mfma_f32_16x16x32_bf16 v[104:107], v[128:131], v[168:171], v[104:107]
	v_mfma_f32_16x16x32_bf16 v[92:95], v[120:123], v[176:179], v[92:95]
	v_mfma_f32_16x16x32_bf16 v[88:91], v[128:131], v[176:179], v[88:91]
	v_mfma_f32_16x16x32_bf16 v[76:79], v[120:123], v[184:187], v[76:79]
	v_mfma_f32_16x16x32_bf16 v[72:75], v[128:131], v[184:187], v[72:75]
	v_mfma_f32_16x16x32_bf16 v[144:147], v[124:127], v[164:167], v[144:147]
	v_mfma_f32_16x16x32_bf16 v[136:139], v[132:135], v[164:167], v[136:139]
	v_mfma_f32_16x16x32_bf16 v[108:111], v[124:127], v[172:175], v[108:111]
	v_mfma_f32_16x16x32_bf16 v[104:107], v[132:135], v[172:175], v[104:107]
	v_mfma_f32_16x16x32_bf16 v[92:95], v[124:127], v[180:183], v[92:95]
	v_mfma_f32_16x16x32_bf16 v[88:91], v[132:135], v[180:183], v[88:91]
	v_mfma_f32_16x16x32_bf16 v[76:79], v[124:127], v[188:191], v[76:79]
	v_mfma_f32_16x16x32_bf16 v[72:75], v[132:135], v[188:191], v[72:75]
	s_setprio 0
	s_setprio 1
	v_mfma_f32_16x16x32_bf16 v[116:119], v[140:143], v[160:163], v[116:119]
	v_mfma_f32_16x16x32_bf16 v[112:115], v[152:155], v[160:163], v[112:115]
	v_mfma_f32_16x16x32_bf16 v[100:103], v[140:143], v[168:171], v[100:103]
	v_mfma_f32_16x16x32_bf16 v[96:99], v[152:155], v[168:171], v[96:99]
	v_mfma_f32_16x16x32_bf16 v[84:87], v[140:143], v[176:179], v[84:87]
	v_mfma_f32_16x16x32_bf16 v[80:83], v[152:155], v[176:179], v[80:83]
	v_mfma_f32_16x16x32_bf16 v[68:71], v[140:143], v[184:187], v[68:71]
	v_mfma_f32_16x16x32_bf16 v[64:67], v[152:155], v[184:187], v[64:67]
	v_mfma_f32_16x16x32_bf16 v[116:119], v[148:151], v[164:167], v[116:119]
	v_mfma_f32_16x16x32_bf16 v[112:115], v[156:159], v[164:167], v[112:115]
	v_mfma_f32_16x16x32_bf16 v[100:103], v[148:151], v[172:175], v[100:103]
	v_mfma_f32_16x16x32_bf16 v[96:99], v[156:159], v[172:175], v[96:99]
	v_mfma_f32_16x16x32_bf16 v[84:87], v[148:151], v[180:183], v[84:87]
	v_mfma_f32_16x16x32_bf16 v[80:83], v[156:159], v[180:183], v[80:83]
	v_mfma_f32_16x16x32_bf16 v[68:71], v[148:151], v[188:191], v[68:71]
	v_mfma_f32_16x16x32_bf16 v[64:67], v[156:159], v[188:191], v[64:67]
	s_barrier
	s_setprio 0
	s_add_i32 s20, s62, s28
	v_lshl_add_u64 v[206:207], v[206:207], 0, s[14:15]
	s_mov_b32 m0, s20
	s_nop 0
	global_load_lds_dwordx4 v[206:207], off
	s_add_i32 m0, s20, 0x2000
	s_add_u32 s20, s24, 0xb0080
	v_lshl_add_u64 v[206:207], v[208:209], 0, s[14:15]
	s_addc_u32 s21, s25, 0
	s_add_i32 s24, s63, s28
	global_load_lds_dwordx4 v[206:207], off
	v_lshl_add_u64 v[206:207], s[20:21], 0, v[194:195]
	s_mov_b32 m0, s24
	s_nop 0
	global_load_lds_dwordx4 v[206:207], off
	v_lshl_add_u64 v[206:207], s[20:21], 0, v[198:199]
	s_add_i32 m0, s24, 0x2000
	s_nop 0
	global_load_lds_dwordx4 v[206:207], off
	v_lshl_add_u64 v[206:207], v[210:211], 0, s[14:15]
	s_mov_b32 m0, s38
	s_nop 0
	global_load_lds_dwordx4 v[206:207], off
	v_lshl_add_u64 v[206:207], v[212:213], 0, s[14:15]
	s_mov_b32 m0, s39
	s_nop 0
	global_load_lds_dwordx4 v[206:207], off
	ds_read_b128 v[160:163], v249 offset:49152
	ds_read_b128 v[164:167], v249 offset:50176
	ds_read_b128 v[168:171], v249 offset:51200
	ds_read_b128 v[172:175], v249 offset:52224
	ds_read_b128 v[176:179], v249 offset:53248
	ds_read_b128 v[180:183], v249 offset:54272
	ds_read_b128 v[184:187], v249 offset:55296
	ds_read_b128 v[188:191], v249 offset:56320
	s_waitcnt vmcnt(8)
	s_waitcnt lgkmcnt(0)
	s_setprio 1
	s_barrier
	v_mfma_f32_16x16x32_bf16 v[60:63], v[120:123], v[160:163], v[60:63]
	v_mfma_f32_16x16x32_bf16 v[56:59], v[128:131], v[160:163], v[56:59]
	v_mfma_f32_16x16x32_bf16 v[44:47], v[120:123], v[168:171], v[44:47]
	v_mfma_f32_16x16x32_bf16 v[40:43], v[128:131], v[168:171], v[40:43]
	v_mfma_f32_16x16x32_bf16 v[28:31], v[120:123], v[176:179], v[28:31]
	v_mfma_f32_16x16x32_bf16 v[24:27], v[128:131], v[176:179], v[24:27]
	v_mfma_f32_16x16x32_bf16 v[12:15], v[120:123], v[184:187], v[12:15]
	v_mfma_f32_16x16x32_bf16 v[8:11], v[128:131], v[184:187], v[8:11]
	v_mfma_f32_16x16x32_bf16 v[60:63], v[124:127], v[164:167], v[60:63]
	v_mfma_f32_16x16x32_bf16 v[56:59], v[132:135], v[164:167], v[56:59]
	v_mfma_f32_16x16x32_bf16 v[44:47], v[124:127], v[172:175], v[44:47]
	v_mfma_f32_16x16x32_bf16 v[40:43], v[132:135], v[172:175], v[40:43]
	v_mfma_f32_16x16x32_bf16 v[28:31], v[124:127], v[180:183], v[28:31]
	v_mfma_f32_16x16x32_bf16 v[24:27], v[132:135], v[180:183], v[24:27]
	v_mfma_f32_16x16x32_bf16 v[12:15], v[124:127], v[188:191], v[12:15]
	v_mfma_f32_16x16x32_bf16 v[8:11], v[132:135], v[188:191], v[8:11]
	s_setprio 0
	s_setprio 1
	v_mfma_f32_16x16x32_bf16 v[52:55], v[140:143], v[160:163], v[52:55]
	v_mfma_f32_16x16x32_bf16 v[48:51], v[152:155], v[160:163], v[48:51]
	v_mfma_f32_16x16x32_bf16 v[36:39], v[140:143], v[168:171], v[36:39]
	v_mfma_f32_16x16x32_bf16 v[32:35], v[152:155], v[168:171], v[32:35]
	v_mfma_f32_16x16x32_bf16 v[20:23], v[140:143], v[176:179], v[20:23]
	v_mfma_f32_16x16x32_bf16 v[16:19], v[152:155], v[176:179], v[16:19]
	v_mfma_f32_16x16x32_bf16 v[4:7], v[140:143], v[184:187], v[4:7]
	v_mfma_f32_16x16x32_bf16 v[0:3], v[152:155], v[184:187], v[0:3]
	v_mfma_f32_16x16x32_bf16 v[52:55], v[148:151], v[164:167], v[52:55]
	v_mfma_f32_16x16x32_bf16 v[48:51], v[156:159], v[164:167], v[48:51]
	v_mfma_f32_16x16x32_bf16 v[36:39], v[148:151], v[172:175], v[36:39]
	v_mfma_f32_16x16x32_bf16 v[32:35], v[156:159], v[172:175], v[32:35]
	v_mfma_f32_16x16x32_bf16 v[20:23], v[148:151], v[180:183], v[20:23]
	v_mfma_f32_16x16x32_bf16 v[16:19], v[156:159], v[180:183], v[16:19]
	v_mfma_f32_16x16x32_bf16 v[4:7], v[148:151], v[188:191], v[4:7]
	v_mfma_f32_16x16x32_bf16 v[0:3], v[156:159], v[188:191], v[0:3]
	s_barrier
	s_setprio 0
	s_add_i32 s61, s61, 2
	s_add_u32 s51, s51, 0x100
	s_addc_u32 s60, s60, 0
	s_cmp_gt_u32 s61, 41
	s_mov_b64 s[20:21], s[22:23]
	s_cbranch_scc0 .LBB0_637
	s_and_b64 vcc, exec, s[16:17]
	s_cbranch_vccz .LBB0_640
	s_barrier

.Lph723_w:
	s_nop 0
	s_nop 0
	s_nop 0
	s_waitcnt vmcnt(8)
	s_waitcnt lgkmcnt(0)
	s_setprio 1
	s_barrier
	v_mfma_f32_16x16x32_bf16 v[124:127], v[128:131], v[160:163], v[124:127]
	v_mfma_f32_16x16x32_bf16 v[120:123], v[136:139], v[160:163], v[120:123]
	v_mfma_f32_16x16x32_bf16 v[116:119], v[128:131], v[168:171], v[116:119]
	v_mfma_f32_16x16x32_bf16 v[112:115], v[136:139], v[168:171], v[112:115]
	v_mfma_f32_16x16x32_bf16 v[108:111], v[128:131], v[176:179], v[108:111]
	v_mfma_f32_16x16x32_bf16 v[100:103], v[136:139], v[176:179], v[100:103]
	v_mfma_f32_16x16x32_bf16 v[92:95], v[128:131], v[184:187], v[92:95]
	v_mfma_f32_16x16x32_bf16 v[80:83], v[136:139], v[184:187], v[80:83]
	v_mfma_f32_16x16x32_bf16 v[124:127], v[132:135], v[164:167], v[124:127]
	v_mfma_f32_16x16x32_bf16 v[120:123], v[140:143], v[164:167], v[120:123]
	v_mfma_f32_16x16x32_bf16 v[116:119], v[132:135], v[172:175], v[116:119]
	v_mfma_f32_16x16x32_bf16 v[112:115], v[140:143], v[172:175], v[112:115]
	v_mfma_f32_16x16x32_bf16 v[108:111], v[132:135], v[180:183], v[108:111]
	v_mfma_f32_16x16x32_bf16 v[100:103], v[140:143], v[180:183], v[100:103]
	v_mfma_f32_16x16x32_bf16 v[92:95], v[132:135], v[188:191], v[92:95]
	v_mfma_f32_16x16x32_bf16 v[80:83], v[140:143], v[188:191], v[80:83]
	s_setprio 0
	s_setprio 1
	v_mfma_f32_16x16x32_bf16 v[104:107], v[144:147], v[160:163], v[104:107]
	v_mfma_f32_16x16x32_bf16 v[96:99], v[152:155], v[160:163], v[96:99]
	v_mfma_f32_16x16x32_bf16 v[88:91], v[144:147], v[168:171], v[88:91]
	v_mfma_f32_16x16x32_bf16 v[84:87], v[152:155], v[168:171], v[84:87]
	v_mfma_f32_16x16x32_bf16 v[76:79], v[144:147], v[176:179], v[76:79]
	v_mfma_f32_16x16x32_bf16 v[72:75], v[152:155], v[176:179], v[72:75]
	v_mfma_f32_16x16x32_bf16 v[68:71], v[144:147], v[184:187], v[68:71]
	v_mfma_f32_16x16x32_bf16 v[64:67], v[152:155], v[184:187], v[64:67]
	v_mfma_f32_16x16x32_bf16 v[104:107], v[148:151], v[164:167], v[104:107]
	v_mfma_f32_16x16x32_bf16 v[96:99], v[156:159], v[164:167], v[96:99]
	v_mfma_f32_16x16x32_bf16 v[88:91], v[148:151], v[172:175], v[88:91]
	v_mfma_f32_16x16x32_bf16 v[84:87], v[156:159], v[172:175], v[84:87]
	v_mfma_f32_16x16x32_bf16 v[76:79], v[148:151], v[180:183], v[76:79]
	v_mfma_f32_16x16x32_bf16 v[72:75], v[156:159], v[180:183], v[72:75]
	v_mfma_f32_16x16x32_bf16 v[68:71], v[148:151], v[188:191], v[68:71]
	v_mfma_f32_16x16x32_bf16 v[64:67], v[156:159], v[188:191], v[64:67]
	s_barrier
	s_setprio 0
	s_add_i32 s94, s88, s68
	v_lshl_add_u64 v[192:193], s[62:63], 0, v[208:209]
	s_mov_b32 m0, s94
	s_nop 0
	global_load_lds_dwordx4 v[192:193], off
	s_add_i32 m0, s94, 0x2000
	s_add_u32 s94, s62, 0x40000
	v_lshl_add_u64 v[194:195], s[62:63], 0, v[212:213]
	s_addc_u32 s95, s63, 0
	s_add_i32 s96, s89, s68
	global_load_lds_dwordx4 v[194:195], off
	v_lshl_add_u64 v[196:197], s[94:95], 0, v[208:209]
	s_mov_b32 m0, s96
	v_lshl_add_u64 v[198:199], s[64:65], 0, v[210:211]
	global_load_lds_dwordx4 v[196:197], off
	v_lshl_add_u64 v[196:197], s[94:95], 0, v[212:213]
	s_add_i32 m0, s96, 0x2000
	s_nop 0
	global_load_lds_dwordx4 v[196:197], off
	v_lshl_add_u64 v[196:197], s[64:65], 0, v[206:207]
	s_mov_b32 m0, s69
	s_nop 0
	global_load_lds_dwordx4 v[196:197], off
	s_mov_b32 m0, s70
	s_nop 0
	global_load_lds_dwordx4 v[198:199], off
	ds_read_b128 v[160:163], v237 offset:16384
	ds_read_b128 v[164:167], v237 offset:17408
	ds_read_b128 v[168:171], v237 offset:18432
	ds_read_b128 v[172:175], v237 offset:19456
	ds_read_b128 v[176:179], v237 offset:20480
	ds_read_b128 v[180:183], v237 offset:21504
	ds_read_b128 v[184:187], v237 offset:22528
	ds_read_b128 v[188:191], v237 offset:23552
	s_nop 0
	s_waitcnt vmcnt(8)
	s_waitcnt lgkmcnt(0)
	s_setprio 1
	s_barrier
	v_mfma_f32_16x16x32_bf16 v[60:63], v[128:131], v[160:163], v[60:63]
	v_mfma_f32_16x16x32_bf16 v[56:59], v[136:139], v[160:163], v[56:59]
	v_mfma_f32_16x16x32_bf16 v[48:51], v[128:131], v[168:171], v[48:51]
	v_mfma_f32_16x16x32_bf16 v[40:43], v[136:139], v[168:171], v[40:43]
	v_mfma_f32_16x16x32_bf16 v[32:35], v[128:131], v[176:179], v[32:35]
	v_mfma_f32_16x16x32_bf16 v[24:27], v[136:139], v[176:179], v[24:27]
	v_mfma_f32_16x16x32_bf16 v[16:19], v[128:131], v[184:187], v[16:19]
	v_mfma_f32_16x16x32_bf16 v[8:11], v[136:139], v[184:187], v[8:11]
	v_mfma_f32_16x16x32_bf16 v[60:63], v[132:135], v[164:167], v[60:63]
	v_mfma_f32_16x16x32_bf16 v[56:59], v[140:143], v[164:167], v[56:59]
	v_mfma_f32_16x16x32_bf16 v[48:51], v[132:135], v[172:175], v[48:51]
	v_mfma_f32_16x16x32_bf16 v[40:43], v[140:143], v[172:175], v[40:43]
	v_mfma_f32_16x16x32_bf16 v[32:35], v[132:135], v[180:183], v[32:35]
	v_mfma_f32_16x16x32_bf16 v[24:27], v[140:143], v[180:183], v[24:27]
	v_mfma_f32_16x16x32_bf16 v[16:19], v[132:135], v[188:191], v[16:19]
	v_mfma_f32_16x16x32_bf16 v[8:11], v[140:143], v[188:191], v[8:11]
	s_setprio 0
	s_setprio 1
	v_mfma_f32_16x16x32_bf16 v[52:55], v[144:147], v[160:163], v[52:55]
	v_mfma_f32_16x16x32_bf16 v[44:47], v[152:155], v[160:163], v[44:47]
	v_mfma_f32_16x16x32_bf16 v[36:39], v[144:147], v[168:171], v[36:39]
	v_mfma_f32_16x16x32_bf16 v[28:31], v[152:155], v[168:171], v[28:31]
	v_mfma_f32_16x16x32_bf16 v[20:23], v[144:147], v[176:179], v[20:23]
	v_mfma_f32_16x16x32_bf16 v[12:15], v[152:155], v[176:179], v[12:15]
	v_mfma_f32_16x16x32_bf16 v[4:7], v[144:147], v[184:187], v[4:7]
	v_mfma_f32_16x16x32_bf16 v[0:3], v[152:155], v[184:187], v[0:3]
	v_mfma_f32_16x16x32_bf16 v[52:55], v[148:151], v[164:167], v[52:55]
	v_mfma_f32_16x16x32_bf16 v[44:47], v[156:159], v[164:167], v[44:47]
	v_mfma_f32_16x16x32_bf16 v[36:39], v[148:151], v[172:175], v[36:39]
	v_mfma_f32_16x16x32_bf16 v[28:31], v[156:159], v[172:175], v[28:31]
	v_mfma_f32_16x16x32_bf16 v[20:23], v[148:151], v[180:183], v[20:23]
	v_mfma_f32_16x16x32_bf16 v[12:15], v[156:159], v[180:183], v[12:15]
	v_mfma_f32_16x16x32_bf16 v[4:7], v[148:151], v[188:191], v[4:7]
	v_mfma_f32_16x16x32_bf16 v[0:3], v[156:159], v[188:191], v[0:3]
	s_barrier
	s_setprio 0
	s_add_i32 s94, 0, 0x18000
	s_add_i32 s95, 0, 0x1c000
	s_add_u32 s64, s64, 0x40000
	s_addc_u32 s65, s65, 0
	s_mov_b32 m0, s71
	v_lshl_add_u64 v[200:201], s[64:65], 0, v[206:207]
	global_load_lds_dwordx4 v[200:201], off
	v_lshl_add_u64 v[200:201], s[64:65], 0, v[210:211]
	s_mov_b32 m0, s72
	s_nop 0
	global_load_lds_dwordx4 v[200:201], off
	v_add_u32_e32 v140, s94, v234
	v_add_u32_e32 v156, s95, v234
	ds_read_b128 v[128:131], v140
	ds_read_b128 v[132:135], v140 offset:1024
	ds_read_b128 v[136:139], v140 offset:2048
	ds_read_b128 v[140:143], v140 offset:3072
	ds_read_b128 v[144:147], v156
	ds_read_b128 v[148:151], v156 offset:1024
	ds_read_b128 v[152:155], v156 offset:2048
	ds_read_b128 v[156:159], v156 offset:3072
	ds_read_b128 v[160:163], v237 offset:32768
	ds_read_b128 v[164:167], v237 offset:33792
	ds_read_b128 v[168:171], v237 offset:34816
	ds_read_b128 v[172:175], v237 offset:35840
	ds_read_b128 v[176:179], v237 offset:36864
	ds_read_b128 v[180:183], v237 offset:37888
	ds_read_b128 v[184:187], v237 offset:38912
	ds_read_b128 v[188:191], v237 offset:39936
	s_waitcnt vmcnt(8)
	s_waitcnt lgkmcnt(0)
	s_setprio 1
	s_barrier
	v_mfma_f32_16x16x32_bf16 v[124:127], v[128:131], v[160:163], v[124:127]
	v_mfma_f32_16x16x32_bf16 v[120:123], v[136:139], v[160:163], v[120:123]
	v_mfma_f32_16x16x32_bf16 v[116:119], v[128:131], v[168:171], v[116:119]
	v_mfma_f32_16x16x32_bf16 v[112:115], v[136:139], v[168:171], v[112:115]
	v_mfma_f32_16x16x32_bf16 v[108:111], v[128:131], v[176:179], v[108:111]
	v_mfma_f32_16x16x32_bf16 v[100:103], v[136:139], v[176:179], v[100:103]
	v_mfma_f32_16x16x32_bf16 v[92:95], v[128:131], v[184:187], v[92:95]
	v_mfma_f32_16x16x32_bf16 v[80:83], v[136:139], v[184:187], v[80:83]
	v_mfma_f32_16x16x32_bf16 v[124:127], v[132:135], v[164:167], v[124:127]
	v_mfma_f32_16x16x32_bf16 v[120:123], v[140:143], v[164:167], v[120:123]
	v_mfma_f32_16x16x32_bf16 v[116:119], v[132:135], v[172:175], v[116:119]
	v_mfma_f32_16x16x32_bf16 v[112:115], v[140:143], v[172:175], v[112:115]
	v_mfma_f32_16x16x32_bf16 v[108:111], v[132:135], v[180:183], v[108:111]
	v_mfma_f32_16x16x32_bf16 v[100:103], v[140:143], v[180:183], v[100:103]
	v_mfma_f32_16x16x32_bf16 v[92:95], v[132:135], v[188:191], v[92:95]
	v_mfma_f32_16x16x32_bf16 v[80:83], v[140:143], v[188:191], v[80:83]
	s_setprio 0
	s_setprio 1
	v_mfma_f32_16x16x32_bf16 v[104:107], v[144:147], v[160:163], v[104:107]
	v_mfma_f32_16x16x32_bf16 v[96:99], v[152:155], v[160:163], v[96:99]
	v_mfma_f32_16x16x32_bf16 v[88:91], v[144:147], v[168:171], v[88:91]
	v_mfma_f32_16x16x32_bf16 v[84:87], v[152:155], v[168:171], v[84:87]
	v_mfma_f32_16x16x32_bf16 v[76:79], v[144:147], v[176:179], v[76:79]
	v_mfma_f32_16x16x32_bf16 v[72:75], v[152:155], v[176:179], v[72:75]
	v_mfma_f32_16x16x32_bf16 v[68:71], v[144:147], v[184:187], v[68:71]
	v_mfma_f32_16x16x32_bf16 v[64:67], v[152:155], v[184:187], v[64:67]
	v_mfma_f32_16x16x32_bf16 v[104:107], v[148:151], v[164:167], v[104:107]
	v_mfma_f32_16x16x32_bf16 v[96:99], v[156:159], v[164:167], v[96:99]
	v_mfma_f32_16x16x32_bf16 v[88:91], v[148:151], v[172:175], v[88:91]
	v_mfma_f32_16x16x32_bf16 v[84:87], v[156:159], v[172:175], v[84:87]
	v_mfma_f32_16x16x32_bf16 v[76:79], v[148:151], v[180:183], v[76:79]
	v_mfma_f32_16x16x32_bf16 v[72:75], v[156:159], v[180:183], v[72:75]
	v_mfma_f32_16x16x32_bf16 v[68:71], v[148:151], v[188:191], v[68:71]
	v_mfma_f32_16x16x32_bf16 v[64:67], v[156:159], v[188:191], v[64:67]
	s_barrier
	s_setprio 0
	s_add_i32 s64, s94, s68
	v_lshl_add_u64 v[192:193], v[192:193], 0, s[14:15]
	s_mov_b32 m0, s64
	s_nop 0
	global_load_lds_dwordx4 v[192:193], off
	s_add_i32 m0, s64, 0x2000
	s_add_u32 s62, s62, 0x40080
	v_lshl_add_u64 v[192:193], v[194:195], 0, s[14:15]
	s_addc_u32 s63, s63, 0
	s_add_i32 s64, s95, s68
	global_load_lds_dwordx4 v[192:193], off
	v_lshl_add_u64 v[192:193], s[62:63], 0, v[208:209]
	s_mov_b32 m0, s64
	s_nop 0
	global_load_lds_dwordx4 v[192:193], off
	v_lshl_add_u64 v[192:193], s[62:63], 0, v[212:213]
	s_add_i32 m0, s64, 0x2000
	s_nop 0
	global_load_lds_dwordx4 v[192:193], off
	v_lshl_add_u64 v[192:193], v[196:197], 0, s[14:15]
	s_mov_b32 m0, s76
	s_nop 0
	global_load_lds_dwordx4 v[192:193], off
	v_lshl_add_u64 v[192:193], v[198:199], 0, s[14:15]
	s_mov_b32 m0, s77
	s_nop 0
	global_load_lds_dwordx4 v[192:193], off
	ds_read_b128 v[160:163], v237 offset:49152
	ds_read_b128 v[164:167], v237 offset:50176
	ds_read_b128 v[168:171], v237 offset:51200
	ds_read_b128 v[172:175], v237 offset:52224
	ds_read_b128 v[176:179], v237 offset:53248
	ds_read_b128 v[180:183], v237 offset:54272
	ds_read_b128 v[184:187], v237 offset:55296
	ds_read_b128 v[188:191], v237 offset:56320
	s_waitcnt vmcnt(8)
	s_waitcnt lgkmcnt(0)
	s_setprio 1
	s_barrier
	v_mfma_f32_16x16x32_bf16 v[60:63], v[128:131], v[160:163], v[60:63]
	v_mfma_f32_16x16x32_bf16 v[56:59], v[136:139], v[160:163], v[56:59]
	v_mfma_f32_16x16x32_bf16 v[48:51], v[128:131], v[168:171], v[48:51]
	v_mfma_f32_16x16x32_bf16 v[40:43], v[136:139], v[168:171], v[40:43]
	v_mfma_f32_16x16x32_bf16 v[32:35], v[128:131], v[176:179], v[32:35]
	v_mfma_f32_16x16x32_bf16 v[24:27], v[136:139], v[176:179], v[24:27]
	v_mfma_f32_16x16x32_bf16 v[16:19], v[128:131], v[184:187], v[16:19]
	v_mfma_f32_16x16x32_bf16 v[8:11], v[136:139], v[184:187], v[8:11]
	v_mfma_f32_16x16x32_bf16 v[60:63], v[132:135], v[164:167], v[60:63]
	v_mfma_f32_16x16x32_bf16 v[56:59], v[140:143], v[164:167], v[56:59]
	v_mfma_f32_16x16x32_bf16 v[48:51], v[132:135], v[172:175], v[48:51]
	v_mfma_f32_16x16x32_bf16 v[40:43], v[140:143], v[172:175], v[40:43]
	v_mfma_f32_16x16x32_bf16 v[32:35], v[132:135], v[180:183], v[32:35]
	v_mfma_f32_16x16x32_bf16 v[24:27], v[140:143], v[180:183], v[24:27]
	v_mfma_f32_16x16x32_bf16 v[16:19], v[132:135], v[188:191], v[16:19]
	v_mfma_f32_16x16x32_bf16 v[8:11], v[140:143], v[188:191], v[8:11]
	s_setprio 0
	s_setprio 1
	v_mfma_f32_16x16x32_bf16 v[52:55], v[144:147], v[160:163], v[52:55]
	v_mfma_f32_16x16x32_bf16 v[44:47], v[152:155], v[160:163], v[44:47]
	v_mfma_f32_16x16x32_bf16 v[36:39], v[144:147], v[168:171], v[36:39]
	v_mfma_f32_16x16x32_bf16 v[28:31], v[152:155], v[168:171], v[28:31]
	v_mfma_f32_16x16x32_bf16 v[20:23], v[144:147], v[176:179], v[20:23]
	v_mfma_f32_16x16x32_bf16 v[12:15], v[152:155], v[176:179], v[12:15]
	v_mfma_f32_16x16x32_bf16 v[4:7], v[144:147], v[184:187], v[4:7]
	v_mfma_f32_16x16x32_bf16 v[0:3], v[152:155], v[184:187], v[0:3]
	v_mfma_f32_16x16x32_bf16 v[52:55], v[148:151], v[164:167], v[52:55]
	v_mfma_f32_16x16x32_bf16 v[44:47], v[156:159], v[164:167], v[44:47]
	v_mfma_f32_16x16x32_bf16 v[36:39], v[148:151], v[172:175], v[36:39]
	v_mfma_f32_16x16x32_bf16 v[28:31], v[156:159], v[172:175], v[28:31]
	v_mfma_f32_16x16x32_bf16 v[20:23], v[148:151], v[180:183], v[20:23]
	v_mfma_f32_16x16x32_bf16 v[12:15], v[156:159], v[180:183], v[12:15]
	v_mfma_f32_16x16x32_bf16 v[4:7], v[148:151], v[188:191], v[4:7]
	v_mfma_f32_16x16x32_bf16 v[0:3], v[156:159], v[188:191], v[0:3]
	s_barrier
	s_setprio 0
	s_add_i32 s93, s93, 2
	s_add_u32 s48, s48, 0x100
	s_addc_u32 s49, s49, 0
	s_add_u32 s60, s60, 0x100
	s_addc_u32 s61, s61, 0
	s_cmp_gt_u32 s93, 13
	s_cbranch_scc0 .LBB0_723
	s_and_b64 vcc, exec, s[16:17]
	s_cbranch_vccz .LBB0_726
	s_barrier

.LBB0_1003:
	s_or_b64 exec, exec, s[12:13]
	v_cvt_f32_u32_e32 v4, v2
	s_waitcnt vmcnt(0)
	v_readfirstlane_b32 s2, v3
	v_sub_u32_e32 v3, 0, v2
	v_rcp_iflag_f32_e32 v4, v4
	v_add_u32_e32 v5, s2, v1
	v_mul_f32_e32 v4, 0x4f7ffffe, v4
	v_cvt_u32_f32_e32 v4, v4
	v_mul_lo_u32 v1, v3, v4
	v_mul_hi_u32 v1, v4, v1
	v_add_u32_e32 v1, v4, v1
	v_mul_hi_u32 v1, v5, v1
	v_mul_lo_u32 v3, v1, v2
	v_sub_u32_e32 v3, v5, v3
	v_add_u32_e32 v4, 1, v1
	v_cmp_ge_u32_e32 vcc, v3, v2
	s_nop 1
	v_cndmask_b32_e32 v1, v1, v4, vcc
	v_sub_u32_e32 v4, v3, v2
	v_cndmask_b32_e32 v3, v3, v4, vcc
	v_add_u32_e32 v4, 1, v1
	v_cmp_ge_u32_e32 vcc, v3, v2
	v_add_u32_e32 v3, 1, v5
	s_nop 0
	v_cndmask_b32_e32 v1, v1, v4, vcc
	v_mul_lo_u32 v4, v2, v1
	v_add_u32_e32 v2, v4, v2
	v_cmp_ne_u32_e32 vcc, v3, v2
	s_and_saveexec_b64 s[4:5], vcc
	s_xor_b64 s[10:11], exec, s[4:5]
	s_cbranch_execz .LBB0_1017
	s_waitcnt lgkmcnt(0)
	v_mad_u32_u24 v3, v1, v0, v0
	v_mov_b32_e32 v0, 0x3000
	global_load_dword v0, v0, s[54:55] offset:1024 sc1
	s_add_u32 s14, s54, 0x3400
	s_addc_u32 s15, s55, 0
	s_waitcnt vmcnt(0)
	v_cmp_lt_u32_e32 vcc, v0, v3
	s_and_saveexec_b64 s[12:13], vcc
	s_cbranch_execz .LBB0_1016
	s_mov_b32 s2, 1
	s_mov_b64 s[16:17], 0
	v_mov_b32_e32 v0, 0
	s_branch .LBB0_1007

.LBB0_1011:
	global_load_dword v2, v0, s[14:15] sc1
	s_add_i32 s2, s2, 1
	s_mov_b64 s[22:23], -1
	s_waitcnt vmcnt(0)
	v_cmp_ge_u32_e32 vcc, v2, v3
	s_orn2_b64 s[20:21], vcc, exec
	s_branch .LBB0_1006

.LBB0_1020:
	s_or_b64 exec, exec, s[12:13]
	v_cvt_f32_u32_e32 v3, v0
	s_waitcnt vmcnt(0)
	v_readfirstlane_b32 s2, v2
	s_add_u32 s12, s54, 0x3500
	s_addc_u32 s13, s55, 0
	v_rcp_iflag_f32_e32 v3, v3
	v_add_u32_e32 v1, s2, v1
	v_add_u32_e32 v4, 1, v1
	s_mov_b64 s[14:15], -1
	v_mul_f32_e32 v2, 0x4f7ffffe, v3
	v_cvt_u32_f32_e32 v2, v2
	v_sub_u32_e32 v3, 0, v0
	v_mul_lo_u32 v3, v3, v2
	v_mul_hi_u32 v3, v2, v3
	v_add_u32_e32 v2, v2, v3
	v_mul_hi_u32 v2, v1, v2
	v_mul_lo_u32 v3, v2, v0
	v_sub_u32_e32 v1, v1, v3
	v_add_u32_e32 v5, 1, v2
	v_cmp_ge_u32_e32 vcc, v1, v0
	v_sub_u32_e32 v3, v1, v0
	s_nop 0
	v_cndmask_b32_e32 v2, v2, v5, vcc
	v_cndmask_b32_e32 v1, v1, v3, vcc
	v_add_u32_e32 v3, 1, v2
	v_cmp_ge_u32_e32 vcc, v1, v0
	s_nop 1
	v_cndmask_b32_e32 v2, v2, v3, vcc
	v_mul_lo_u32 v1, v0, v2
	v_add_u32_e32 v0, v1, v0
	v_cmp_ne_u32_e32 vcc, v4, v0
	v_mov_b32_e32 v3, v0
	v_mov_b64_e32 v[0:1], s[12:13]
	s_and_saveexec_b64 s[10:11], vcc
	s_cbranch_execz .LBB0_1032
	v_mov_b32_e32 v0, 0
	global_load_dword v1, v0, s[12:13] offset:-256 sc1
	s_mov_b64 s[18:19], 0
	s_waitcnt vmcnt(0)
	v_cmp_lt_u32_e32 vcc, v1, v3
	s_and_saveexec_b64 s[16:17], vcc
	s_cbranch_execz .LBB0_1031
	s_add_u32 s14, s54, 0x200
	s_addc_u32 s15, s55, 0
	s_mov_b32 s2, 1
	s_branch .LBB0_1024

.LBB0_1028:
	global_load_dword v1, v0, s[12:13] offset:-256 sc1
	s_add_i32 s2, s2, 1
	s_mov_b64 s[22:23], -1
	s_waitcnt vmcnt(0)
	v_cmp_ge_u32_e32 vcc, v1, v3
	s_orn2_b64 s[26:27], vcc, exec
	s_branch .LBB0_1023

.Lph1109_w:
	s_nop 0
	s_nop 0
	s_nop 0
	s_nop 0
	s_waitcnt vmcnt(8)
	s_waitcnt lgkmcnt(0)
	s_setprio 1
	s_barrier
	v_mfma_f32_16x16x32_bf16 v[144:147], v[120:123], v[160:163], v[144:147]
	v_mfma_f32_16x16x32_bf16 v[136:139], v[128:131], v[160:163], v[136:139]
	v_mfma_f32_16x16x32_bf16 v[108:111], v[120:123], v[168:171], v[108:111]
	v_mfma_f32_16x16x32_bf16 v[104:107], v[128:131], v[168:171], v[104:107]
	v_mfma_f32_16x16x32_bf16 v[92:95], v[120:123], v[176:179], v[92:95]
	v_mfma_f32_16x16x32_bf16 v[88:91], v[128:131], v[176:179], v[88:91]
	v_mfma_f32_16x16x32_bf16 v[76:79], v[120:123], v[184:187], v[76:79]
	v_mfma_f32_16x16x32_bf16 v[72:75], v[128:131], v[184:187], v[72:75]
	v_mfma_f32_16x16x32_bf16 v[144:147], v[124:127], v[164:167], v[144:147]
	v_mfma_f32_16x16x32_bf16 v[136:139], v[132:135], v[164:167], v[136:139]
	v_mfma_f32_16x16x32_bf16 v[108:111], v[124:127], v[172:175], v[108:111]
	v_mfma_f32_16x16x32_bf16 v[104:107], v[132:135], v[172:175], v[104:107]
	v_mfma_f32_16x16x32_bf16 v[92:95], v[124:127], v[180:183], v[92:95]
	v_mfma_f32_16x16x32_bf16 v[88:91], v[132:135], v[180:183], v[88:91]
	v_mfma_f32_16x16x32_bf16 v[76:79], v[124:127], v[188:191], v[76:79]
	v_mfma_f32_16x16x32_bf16 v[72:75], v[132:135], v[188:191], v[72:75]
	s_setprio 0
	s_setprio 1
	v_mfma_f32_16x16x32_bf16 v[116:119], v[140:143], v[160:163], v[116:119]
	v_mfma_f32_16x16x32_bf16 v[112:115], v[152:155], v[160:163], v[112:115]
	v_mfma_f32_16x16x32_bf16 v[100:103], v[140:143], v[168:171], v[100:103]
	v_mfma_f32_16x16x32_bf16 v[96:99], v[152:155], v[168:171], v[96:99]
	v_mfma_f32_16x16x32_bf16 v[84:87], v[140:143], v[176:179], v[84:87]
	v_mfma_f32_16x16x32_bf16 v[80:83], v[152:155], v[176:179], v[80:83]
	v_mfma_f32_16x16x32_bf16 v[68:71], v[140:143], v[184:187], v[68:71]
	v_mfma_f32_16x16x32_bf16 v[64:67], v[152:155], v[184:187], v[64:67]
	v_mfma_f32_16x16x32_bf16 v[116:119], v[148:151], v[164:167], v[116:119]
	v_mfma_f32_16x16x32_bf16 v[112:115], v[156:159], v[164:167], v[112:115]
	v_mfma_f32_16x16x32_bf16 v[100:103], v[148:151], v[172:175], v[100:103]
	v_mfma_f32_16x16x32_bf16 v[96:99], v[156:159], v[172:175], v[96:99]
	v_mfma_f32_16x16x32_bf16 v[84:87], v[148:151], v[180:183], v[84:87]
	v_mfma_f32_16x16x32_bf16 v[80:83], v[156:159], v[180:183], v[80:83]
	v_mfma_f32_16x16x32_bf16 v[68:71], v[148:151], v[188:191], v[68:71]
	v_mfma_f32_16x16x32_bf16 v[64:67], v[156:159], v[188:191], v[64:67]
	s_barrier
	s_setprio 0
	s_add_i32 s65, s51, s37
	v_lshl_add_u64 v[206:207], s[30:31], 0, v[194:195]
	s_mov_b32 m0, s65
	s_nop 0
	global_load_lds_dwordx4 v[206:207], off
	s_add_i32 m0, s65, 0x2000
	s_add_u32 s66, s30, 0x40000
	v_lshl_add_u64 v[208:209], s[30:31], 0, v[198:199]
	s_addc_u32 s67, s31, 0
	s_add_i32 s65, s60, s37
	global_load_lds_dwordx4 v[208:209], off
	v_lshl_add_u64 v[210:211], s[66:67], 0, v[194:195]
	s_mov_b32 m0, s65
	v_lshl_add_u64 v[212:213], s[34:35], 0, v[196:197]
	global_load_lds_dwordx4 v[210:211], off
	v_lshl_add_u64 v[210:211], s[66:67], 0, v[198:199]
	s_add_i32 m0, s65, 0x2000
	s_nop 0
	global_load_lds_dwordx4 v[210:211], off
	v_lshl_add_u64 v[210:211], s[34:35], 0, v[192:193]
	s_mov_b32 m0, s27
	s_nop 0
	global_load_lds_dwordx4 v[210:211], off
	s_mov_b32 m0, s38
	s_nop 0
	global_load_lds_dwordx4 v[212:213], off
	ds_read_b128 v[160:163], v248 offset:16384
	ds_read_b128 v[164:167], v248 offset:17408
	ds_read_b128 v[168:171], v248 offset:18432
	ds_read_b128 v[172:175], v248 offset:19456
	ds_read_b128 v[176:179], v248 offset:20480
	ds_read_b128 v[180:183], v248 offset:21504
	ds_read_b128 v[184:187], v248 offset:22528
	ds_read_b128 v[188:191], v248 offset:23552
	s_nop 0
	s_waitcnt vmcnt(8)
	s_waitcnt lgkmcnt(0)
	s_setprio 1
	s_barrier
	v_mfma_f32_16x16x32_bf16 v[60:63], v[120:123], v[160:163], v[60:63]
	v_mfma_f32_16x16x32_bf16 v[56:59], v[128:131], v[160:163], v[56:59]
	v_mfma_f32_16x16x32_bf16 v[44:47], v[120:123], v[168:171], v[44:47]
	v_mfma_f32_16x16x32_bf16 v[40:43], v[128:131], v[168:171], v[40:43]
	v_mfma_f32_16x16x32_bf16 v[28:31], v[120:123], v[176:179], v[28:31]
	v_mfma_f32_16x16x32_bf16 v[24:27], v[128:131], v[176:179], v[24:27]
	v_mfma_f32_16x16x32_bf16 v[12:15], v[120:123], v[184:187], v[12:15]
	v_mfma_f32_16x16x32_bf16 v[8:11], v[128:131], v[184:187], v[8:11]
	v_mfma_f32_16x16x32_bf16 v[60:63], v[124:127], v[164:167], v[60:63]
	v_mfma_f32_16x16x32_bf16 v[56:59], v[132:135], v[164:167], v[56:59]
	v_mfma_f32_16x16x32_bf16 v[44:47], v[124:127], v[172:175], v[44:47]
	v_mfma_f32_16x16x32_bf16 v[40:43], v[132:135], v[172:175], v[40:43]
	v_mfma_f32_16x16x32_bf16 v[28:31], v[124:127], v[180:183], v[28:31]
	v_mfma_f32_16x16x32_bf16 v[24:27], v[132:135], v[180:183], v[24:27]
	v_mfma_f32_16x16x32_bf16 v[12:15], v[124:127], v[188:191], v[12:15]
	v_mfma_f32_16x16x32_bf16 v[8:11], v[132:135], v[188:191], v[8:11]
	s_setprio 0
	s_setprio 1
	v_mfma_f32_16x16x32_bf16 v[52:55], v[140:143], v[160:163], v[52:55]
	v_mfma_f32_16x16x32_bf16 v[48:51], v[152:155], v[160:163], v[48:51]
	v_mfma_f32_16x16x32_bf16 v[36:39], v[140:143], v[168:171], v[36:39]
	v_mfma_f32_16x16x32_bf16 v[32:35], v[152:155], v[168:171], v[32:35]
	v_mfma_f32_16x16x32_bf16 v[20:23], v[140:143], v[176:179], v[20:23]
	v_mfma_f32_16x16x32_bf16 v[16:19], v[152:155], v[176:179], v[16:19]
	v_mfma_f32_16x16x32_bf16 v[4:7], v[140:143], v[184:187], v[4:7]
	v_mfma_f32_16x16x32_bf16 v[0:3], v[152:155], v[184:187], v[0:3]
	v_mfma_f32_16x16x32_bf16 v[52:55], v[148:151], v[164:167], v[52:55]
	v_mfma_f32_16x16x32_bf16 v[48:51], v[156:159], v[164:167], v[48:51]
	v_mfma_f32_16x16x32_bf16 v[36:39], v[148:151], v[172:175], v[36:39]
	v_mfma_f32_16x16x32_bf16 v[32:35], v[156:159], v[172:175], v[32:35]
	v_mfma_f32_16x16x32_bf16 v[20:23], v[148:151], v[180:183], v[20:23]
	v_mfma_f32_16x16x32_bf16 v[16:19], v[156:159], v[180:183], v[16:19]
	v_mfma_f32_16x16x32_bf16 v[4:7], v[148:151], v[188:191], v[4:7]
	v_mfma_f32_16x16x32_bf16 v[0:3], v[156:159], v[188:191], v[0:3]
	s_barrier
	s_setprio 0
	s_add_i32 s65, 0, 0x18000
	s_add_i32 s66, 0, 0x1c000
	s_add_u32 s34, s34, 0x40000
	s_addc_u32 s35, s35, 0
	s_mov_b32 m0, s39
	v_lshl_add_u64 v[214:215], s[34:35], 0, v[192:193]
	global_load_lds_dwordx4 v[214:215], off
	v_lshl_add_u64 v[214:215], s[34:35], 0, v[196:197]
	s_mov_b32 m0, s40
	s_nop 0
	global_load_lds_dwordx4 v[214:215], off
	v_add_u32_e32 v132, s65, v245
	v_add_u32_e32 v156, s66, v245
	ds_read_b128 v[120:123], v132
	ds_read_b128 v[124:127], v132 offset:1024
	ds_read_b128 v[128:131], v132 offset:2048
	ds_read_b128 v[132:135], v132 offset:3072
	ds_read_b128 v[140:143], v156
	ds_read_b128 v[148:151], v156 offset:1024
	ds_read_b128 v[152:155], v156 offset:2048
	ds_read_b128 v[156:159], v156 offset:3072
	ds_read_b128 v[160:163], v248 offset:32768
	ds_read_b128 v[164:167], v248 offset:33792
	ds_read_b128 v[168:171], v248 offset:34816
	ds_read_b128 v[172:175], v248 offset:35840
	ds_read_b128 v[176:179], v248 offset:36864
	ds_read_b128 v[180:183], v248 offset:37888
	ds_read_b128 v[184:187], v248 offset:38912
	ds_read_b128 v[188:191], v248 offset:39936
	s_waitcnt vmcnt(8)
	s_waitcnt lgkmcnt(0)
	s_setprio 1
	s_barrier
	v_mfma_f32_16x16x32_bf16 v[144:147], v[120:123], v[160:163], v[144:147]
	v_mfma_f32_16x16x32_bf16 v[136:139], v[128:131], v[160:163], v[136:139]
	v_mfma_f32_16x16x32_bf16 v[108:111], v[120:123], v[168:171], v[108:111]
	v_mfma_f32_16x16x32_bf16 v[104:107], v[128:131], v[168:171], v[104:107]
	v_mfma_f32_16x16x32_bf16 v[92:95], v[120:123], v[176:179], v[92:95]
	v_mfma_f32_16x16x32_bf16 v[88:91], v[128:131], v[176:179], v[88:91]
	v_mfma_f32_16x16x32_bf16 v[76:79], v[120:123], v[184:187], v[76:79]
	v_mfma_f32_16x16x32_bf16 v[72:75], v[128:131], v[184:187], v[72:75]
	v_mfma_f32_16x16x32_bf16 v[144:147], v[124:127], v[164:167], v[144:147]
	v_mfma_f32_16x16x32_bf16 v[136:139], v[132:135], v[164:167], v[136:139]
	v_mfma_f32_16x16x32_bf16 v[108:111], v[124:127], v[172:175], v[108:111]
	v_mfma_f32_16x16x32_bf16 v[104:107], v[132:135], v[172:175], v[104:107]
	v_mfma_f32_16x16x32_bf16 v[92:95], v[124:127], v[180:183], v[92:95]
	v_mfma_f32_16x16x32_bf16 v[88:91], v[132:135], v[180:183], v[88:91]
	v_mfma_f32_16x16x32_bf16 v[76:79], v[124:127], v[188:191], v[76:79]
	v_mfma_f32_16x16x32_bf16 v[72:75], v[132:135], v[188:191], v[72:75]
	s_setprio 0
	s_setprio 1
	v_mfma_f32_16x16x32_bf16 v[116:119], v[140:143], v[160:163], v[116:119]
	v_mfma_f32_16x16x32_bf16 v[112:115], v[152:155], v[160:163], v[112:115]
	v_mfma_f32_16x16x32_bf16 v[100:103], v[140:143], v[168:171], v[100:103]
	v_mfma_f32_16x16x32_bf16 v[96:99], v[152:155], v[168:171], v[96:99]
	v_mfma_f32_16x16x32_bf16 v[84:87], v[140:143], v[176:179], v[84:87]
	v_mfma_f32_16x16x32_bf16 v[80:83], v[152:155], v[176:179], v[80:83]
	v_mfma_f32_16x16x32_bf16 v[68:71], v[140:143], v[184:187], v[68:71]
	v_mfma_f32_16x16x32_bf16 v[64:67], v[152:155], v[184:187], v[64:67]
	v_mfma_f32_16x16x32_bf16 v[116:119], v[148:151], v[164:167], v[116:119]
	v_mfma_f32_16x16x32_bf16 v[112:115], v[156:159], v[164:167], v[112:115]
	v_mfma_f32_16x16x32_bf16 v[100:103], v[148:151], v[172:175], v[100:103]
	v_mfma_f32_16x16x32_bf16 v[96:99], v[156:159], v[172:175], v[96:99]
	v_mfma_f32_16x16x32_bf16 v[84:87], v[148:151], v[180:183], v[84:87]
	v_mfma_f32_16x16x32_bf16 v[80:83], v[156:159], v[180:183], v[80:83]
	v_mfma_f32_16x16x32_bf16 v[68:71], v[148:151], v[188:191], v[68:71]
	v_mfma_f32_16x16x32_bf16 v[64:67], v[156:159], v[188:191], v[64:67]
	s_barrier
	s_setprio 0
	s_add_i32 s34, s65, s37
	v_lshl_add_u64 v[206:207], v[206:207], 0, s[12:13]
	s_mov_b32 m0, s34
	s_nop 0
	global_load_lds_dwordx4 v[206:207], off
	s_add_i32 m0, s34, 0x2000
	s_add_u32 s30, s30, 0x40080
	v_lshl_add_u64 v[206:207], v[208:209], 0, s[12:13]
	s_addc_u32 s31, s31, 0
	s_add_i32 s34, s66, s37
	global_load_lds_dwordx4 v[206:207], off
	v_lshl_add_u64 v[206:207], s[30:31], 0, v[194:195]
	s_mov_b32 m0, s34
	s_nop 0
	global_load_lds_dwordx4 v[206:207], off
	v_lshl_add_u64 v[206:207], s[30:31], 0, v[198:199]
	s_add_i32 m0, s34, 0x2000
	s_nop 0
	global_load_lds_dwordx4 v[206:207], off
	v_lshl_add_u64 v[206:207], v[210:211], 0, s[12:13]
	s_mov_b32 m0, s46
	s_nop 0
	global_load_lds_dwordx4 v[206:207], off
	v_lshl_add_u64 v[206:207], v[212:213], 0, s[12:13]
	s_mov_b32 m0, s47
	s_nop 0
	global_load_lds_dwordx4 v[206:207], off
	ds_read_b128 v[160:163], v248 offset:49152
	ds_read_b128 v[164:167], v248 offset:50176
	ds_read_b128 v[168:171], v248 offset:51200
	ds_read_b128 v[172:175], v248 offset:52224
	ds_read_b128 v[176:179], v248 offset:53248
	ds_read_b128 v[180:183], v248 offset:54272
	ds_read_b128 v[184:187], v248 offset:55296
	ds_read_b128 v[188:191], v248 offset:56320
	s_waitcnt vmcnt(8)
	s_waitcnt lgkmcnt(0)
	s_setprio 1
	s_barrier
	v_mfma_f32_16x16x32_bf16 v[60:63], v[120:123], v[160:163], v[60:63]
	v_mfma_f32_16x16x32_bf16 v[56:59], v[128:131], v[160:163], v[56:59]
	v_mfma_f32_16x16x32_bf16 v[44:47], v[120:123], v[168:171], v[44:47]
	v_mfma_f32_16x16x32_bf16 v[40:43], v[128:131], v[168:171], v[40:43]
	v_mfma_f32_16x16x32_bf16 v[28:31], v[120:123], v[176:179], v[28:31]
	v_mfma_f32_16x16x32_bf16 v[24:27], v[128:131], v[176:179], v[24:27]
	v_mfma_f32_16x16x32_bf16 v[12:15], v[120:123], v[184:187], v[12:15]
	v_mfma_f32_16x16x32_bf16 v[8:11], v[128:131], v[184:187], v[8:11]
	v_mfma_f32_16x16x32_bf16 v[60:63], v[124:127], v[164:167], v[60:63]
	v_mfma_f32_16x16x32_bf16 v[56:59], v[132:135], v[164:167], v[56:59]
	v_mfma_f32_16x16x32_bf16 v[44:47], v[124:127], v[172:175], v[44:47]
	v_mfma_f32_16x16x32_bf16 v[40:43], v[132:135], v[172:175], v[40:43]
	v_mfma_f32_16x16x32_bf16 v[28:31], v[124:127], v[180:183], v[28:31]
	v_mfma_f32_16x16x32_bf16 v[24:27], v[132:135], v[180:183], v[24:27]
	v_mfma_f32_16x16x32_bf16 v[12:15], v[124:127], v[188:191], v[12:15]
	v_mfma_f32_16x16x32_bf16 v[8:11], v[132:135], v[188:191], v[8:11]
	s_setprio 0
	s_setprio 1
	v_mfma_f32_16x16x32_bf16 v[52:55], v[140:143], v[160:163], v[52:55]
	v_mfma_f32_16x16x32_bf16 v[48:51], v[152:155], v[160:163], v[48:51]
	v_mfma_f32_16x16x32_bf16 v[36:39], v[140:143], v[168:171], v[36:39]
	v_mfma_f32_16x16x32_bf16 v[32:35], v[152:155], v[168:171], v[32:35]
	v_mfma_f32_16x16x32_bf16 v[20:23], v[140:143], v[176:179], v[20:23]
	v_mfma_f32_16x16x32_bf16 v[16:19], v[152:155], v[176:179], v[16:19]
	v_mfma_f32_16x16x32_bf16 v[4:7], v[140:143], v[184:187], v[4:7]
	v_mfma_f32_16x16x32_bf16 v[0:3], v[152:155], v[184:187], v[0:3]
	v_mfma_f32_16x16x32_bf16 v[52:55], v[148:151], v[164:167], v[52:55]
	v_mfma_f32_16x16x32_bf16 v[48:51], v[156:159], v[164:167], v[48:51]
	v_mfma_f32_16x16x32_bf16 v[36:39], v[148:151], v[172:175], v[36:39]
	v_mfma_f32_16x16x32_bf16 v[32:35], v[156:159], v[172:175], v[32:35]
	v_mfma_f32_16x16x32_bf16 v[20:23], v[148:151], v[180:183], v[20:23]
	v_mfma_f32_16x16x32_bf16 v[16:19], v[156:159], v[180:183], v[16:19]
	v_mfma_f32_16x16x32_bf16 v[4:7], v[148:151], v[188:191], v[4:7]
	v_mfma_f32_16x16x32_bf16 v[0:3], v[156:159], v[188:191], v[0:3]
	s_barrier
	s_setprio 0
	s_add_i32 s64, s64, 2
	s_add_u32 s28, s28, 0x100
	s_addc_u32 s29, s29, 0
	s_add_u32 s62, s62, 0x100
	s_addc_u32 s63, s63, 0
	s_cmp_gt_u32 s64, 13
	s_cbranch_scc0 .LBB0_1109
	s_and_b64 vcc, exec, s[14:15]
	s_cbranch_vccz .LBB0_1112
	s_barrier

.LBB0_1150:
	s_or_b64 exec, exec, s[14:15]
	v_cvt_f32_u32_e32 v4, v2
	s_waitcnt vmcnt(0)
	v_readfirstlane_b32 s2, v3
	v_sub_u32_e32 v3, 0, v2
	v_rcp_iflag_f32_e32 v4, v4
	v_add_u32_e32 v5, s2, v1
	v_mul_f32_e32 v4, 0x4f7ffffe, v4
	v_cvt_u32_f32_e32 v4, v4
	v_mul_lo_u32 v1, v3, v4
	v_mul_hi_u32 v1, v4, v1
	v_add_u32_e32 v1, v4, v1
	v_mul_hi_u32 v1, v5, v1
	v_mul_lo_u32 v3, v1, v2
	v_sub_u32_e32 v3, v5, v3
	v_add_u32_e32 v4, 1, v1
	v_cmp_ge_u32_e32 vcc, v3, v2
	s_nop 1
	v_cndmask_b32_e32 v1, v1, v4, vcc
	v_sub_u32_e32 v4, v3, v2
	v_cndmask_b32_e32 v3, v3, v4, vcc
	v_add_u32_e32 v4, 1, v1
	v_cmp_ge_u32_e32 vcc, v3, v2
	v_add_u32_e32 v3, 1, v5
	s_nop 0
	v_cndmask_b32_e32 v1, v1, v4, vcc
	v_mul_lo_u32 v4, v2, v1
	v_add_u32_e32 v2, v4, v2
	v_cmp_ne_u32_e32 vcc, v3, v2
	s_and_saveexec_b64 s[4:5], vcc
	s_xor_b64 s[12:13], exec, s[4:5]
	s_cbranch_execz .LBB0_1164
	s_waitcnt lgkmcnt(0)
	v_mad_u32_u24 v3, v1, v0, v0
	v_mov_b32_e32 v0, 0x3000
	global_load_dword v0, v0, s[54:55] offset:1024 sc1
	s_add_u32 s16, s54, 0x3400
	s_addc_u32 s17, s55, 0
	s_waitcnt vmcnt(0)
	v_cmp_lt_u32_e32 vcc, v0, v3
	s_and_saveexec_b64 s[14:15], vcc
	s_cbranch_execz .LBB0_1163
	s_mov_b32 s2, 1
	s_mov_b64 s[18:19], 0
	v_mov_b32_e32 v0, 0
	s_branch .LBB0_1154

.LBB0_1158:
	global_load_dword v2, v0, s[16:17] sc1
	s_add_i32 s2, s2, 1
	s_mov_b64 s[24:25], -1
	s_waitcnt vmcnt(0)
	v_cmp_ge_u32_e32 vcc, v2, v3
	s_orn2_b64 s[22:23], vcc, exec
	s_branch .LBB0_1153

.LBB0_1167:
	s_or_b64 exec, exec, s[14:15]
	v_cvt_f32_u32_e32 v3, v0
	s_waitcnt vmcnt(0)
	v_readfirstlane_b32 s2, v2
	s_add_u32 s14, s54, 0x3500
	s_addc_u32 s15, s55, 0
	v_rcp_iflag_f32_e32 v3, v3
	v_add_u32_e32 v1, s2, v1
	v_add_u32_e32 v4, 1, v1
	s_mov_b64 s[16:17], -1
	v_mul_f32_e32 v2, 0x4f7ffffe, v3
	v_cvt_u32_f32_e32 v2, v2
	v_sub_u32_e32 v3, 0, v0
	v_mul_lo_u32 v3, v3, v2
	v_mul_hi_u32 v3, v2, v3
	v_add_u32_e32 v2, v2, v3
	v_mul_hi_u32 v2, v1, v2
	v_mul_lo_u32 v3, v2, v0
	v_sub_u32_e32 v1, v1, v3
	v_add_u32_e32 v5, 1, v2
	v_cmp_ge_u32_e32 vcc, v1, v0
	v_sub_u32_e32 v3, v1, v0
	s_nop 0
	v_cndmask_b32_e32 v2, v2, v5, vcc
	v_cndmask_b32_e32 v1, v1, v3, vcc
	v_add_u32_e32 v3, 1, v2
	v_cmp_ge_u32_e32 vcc, v1, v0
	s_nop 1
	v_cndmask_b32_e32 v2, v2, v3, vcc
	v_mul_lo_u32 v1, v0, v2
	v_add_u32_e32 v0, v1, v0
	v_cmp_ne_u32_e32 vcc, v4, v0
	v_mov_b32_e32 v3, v0
	v_mov_b64_e32 v[0:1], s[14:15]
	s_and_saveexec_b64 s[12:13], vcc
	s_cbranch_execz .LBB0_1179
	v_mov_b32_e32 v0, 0
	global_load_dword v1, v0, s[14:15] offset:-256 sc1
	s_mov_b64 s[20:21], 0
	s_waitcnt vmcnt(0)
	v_cmp_lt_u32_e32 vcc, v1, v3
	s_and_saveexec_b64 s[18:19], vcc
	s_cbranch_execz .LBB0_1178
	s_add_u32 s16, s54, 0x200
	s_addc_u32 s17, s55, 0
	s_mov_b32 s2, 1
	s_branch .LBB0_1171

.LBB0_1175:
	global_load_dword v1, v0, s[14:15] offset:-256 sc1
	s_add_i32 s2, s2, 1
	s_mov_b64 s[24:25], -1
	s_waitcnt vmcnt(0)
	v_cmp_ge_u32_e32 vcc, v1, v3
	s_orn2_b64 s[28:29], vcc, exec
	s_branch .LBB0_1170

.Lph1193_w:
	s_nop 0
	s_nop 0
	s_waitcnt vmcnt(8)
	s_waitcnt lgkmcnt(0)
	s_setprio 1
	s_barrier
	v_mfma_f32_16x16x32_bf16 v[116:119], v[154:157], v[186:189], v[116:119]
	v_mfma_f32_16x16x32_bf16 v[112:115], v[162:165], v[186:189], v[112:115]
	v_mfma_f32_16x16x32_bf16 v[108:111], v[154:157], v[194:197], v[108:111]
	v_mfma_f32_16x16x32_bf16 v[100:103], v[162:165], v[194:197], v[100:103]
	v_mfma_f32_16x16x32_bf16 v[92:95], v[154:157], v[202:205], v[92:95]
	v_mfma_f32_16x16x32_bf16 v[84:87], v[162:165], v[202:205], v[84:87]
	v_mfma_f32_16x16x32_bf16 v[76:79], v[154:157], v[210:213], v[76:79]
	v_mfma_f32_16x16x32_bf16 v[68:71], v[162:165], v[210:213], v[68:71]
	v_mfma_f32_16x16x32_bf16 v[116:119], v[158:161], v[190:193], v[116:119]
	v_mfma_f32_16x16x32_bf16 v[112:115], v[166:169], v[190:193], v[112:115]
	v_mfma_f32_16x16x32_bf16 v[108:111], v[158:161], v[198:201], v[108:111]
	v_mfma_f32_16x16x32_bf16 v[100:103], v[166:169], v[198:201], v[100:103]
	v_mfma_f32_16x16x32_bf16 v[92:95], v[158:161], v[206:209], v[92:95]
	v_mfma_f32_16x16x32_bf16 v[84:87], v[166:169], v[206:209], v[84:87]
	v_mfma_f32_16x16x32_bf16 v[76:79], v[158:161], v[214:217], v[76:79]
	v_mfma_f32_16x16x32_bf16 v[68:71], v[166:169], v[214:217], v[68:71]
	s_setprio 0
	s_setprio 1
	v_mfma_f32_16x16x32_bf16 v[124:127], v[170:173], v[186:189], v[124:127]
	v_mfma_f32_16x16x32_bf16 v[120:123], v[178:181], v[186:189], v[120:123]
	v_mfma_f32_16x16x32_bf16 v[104:107], v[170:173], v[194:197], v[104:107]
	v_mfma_f32_16x16x32_bf16 v[96:99], v[178:181], v[194:197], v[96:99]
	v_mfma_f32_16x16x32_bf16 v[88:91], v[170:173], v[202:205], v[88:91]
	v_mfma_f32_16x16x32_bf16 v[80:83], v[178:181], v[202:205], v[80:83]
	v_mfma_f32_16x16x32_bf16 v[72:75], v[170:173], v[210:213], v[72:75]
	v_mfma_f32_16x16x32_bf16 v[64:67], v[178:181], v[210:213], v[64:67]
	v_mfma_f32_16x16x32_bf16 v[124:127], v[174:177], v[190:193], v[124:127]
	v_mfma_f32_16x16x32_bf16 v[120:123], v[182:185], v[190:193], v[120:123]
	v_mfma_f32_16x16x32_bf16 v[104:107], v[174:177], v[198:201], v[104:107]
	v_mfma_f32_16x16x32_bf16 v[96:99], v[182:185], v[198:201], v[96:99]
	v_mfma_f32_16x16x32_bf16 v[88:91], v[174:177], v[206:209], v[88:91]
	v_mfma_f32_16x16x32_bf16 v[80:83], v[182:185], v[206:209], v[80:83]
	v_mfma_f32_16x16x32_bf16 v[72:75], v[174:177], v[214:217], v[72:75]
	v_mfma_f32_16x16x32_bf16 v[64:67], v[182:185], v[214:217], v[64:67]
	s_barrier
	s_setprio 0
	s_add_i32 s63, s47, s5
	v_lshl_add_u64 v[144:145], s[30:31], 0, v[132:133]
	s_mov_b32 m0, s63
	s_nop 0
	global_load_lds_dwordx4 v[144:145], off
	s_add_i32 m0, s63, 0x2000
	s_add_u32 s64, s30, 0x40000
	v_lshl_add_u64 v[218:219], s[30:31], 0, v[128:129]
	s_addc_u32 s65, s31, 0
	s_add_i32 s63, s48, s5
	global_load_lds_dwordx4 v[218:219], off
	v_lshl_add_u64 v[220:221], s[64:65], 0, v[132:133]
	s_mov_b32 m0, s63
	v_lshl_add_u64 v[222:223], s[34:35], 0, v[130:131]
	global_load_lds_dwordx4 v[220:221], off
	v_lshl_add_u64 v[220:221], s[64:65], 0, v[128:129]
	s_add_i32 m0, s63, 0x2000
	s_nop 0
	global_load_lds_dwordx4 v[220:221], off
	v_lshl_add_u64 v[220:221], s[34:35], 0, v[134:135]
	s_mov_b32 m0, s25
	s_nop 0
	global_load_lds_dwordx4 v[220:221], off
	s_mov_b32 m0, s27
	s_nop 0
	global_load_lds_dwordx4 v[222:223], off
	ds_read_b128 v[186:189], v151 offset:16384
	ds_read_b128 v[190:193], v151 offset:17408
	ds_read_b128 v[194:197], v151 offset:18432
	ds_read_b128 v[198:201], v151 offset:19456
	ds_read_b128 v[202:205], v151 offset:20480
	ds_read_b128 v[206:209], v151 offset:21504
	ds_read_b128 v[210:213], v151 offset:22528
	ds_read_b128 v[214:217], v151 offset:23552
	s_nop 0
	s_waitcnt vmcnt(8)
	s_waitcnt lgkmcnt(0)
	s_setprio 1
	s_barrier
	v_mfma_f32_16x16x32_bf16 v[60:63], v[154:157], v[186:189], v[60:63]
	v_mfma_f32_16x16x32_bf16 v[52:55], v[162:165], v[186:189], v[52:55]
	v_mfma_f32_16x16x32_bf16 v[44:47], v[154:157], v[194:197], v[44:47]
	v_mfma_f32_16x16x32_bf16 v[36:39], v[162:165], v[194:197], v[36:39]
	v_mfma_f32_16x16x32_bf16 v[28:31], v[154:157], v[202:205], v[28:31]
	v_mfma_f32_16x16x32_bf16 v[20:23], v[162:165], v[202:205], v[20:23]
	v_mfma_f32_16x16x32_bf16 v[12:15], v[154:157], v[210:213], v[12:15]
	v_mfma_f32_16x16x32_bf16 v[4:7], v[162:165], v[210:213], v[4:7]
	v_mfma_f32_16x16x32_bf16 v[60:63], v[158:161], v[190:193], v[60:63]
	v_mfma_f32_16x16x32_bf16 v[52:55], v[166:169], v[190:193], v[52:55]
	v_mfma_f32_16x16x32_bf16 v[44:47], v[158:161], v[198:201], v[44:47]
	v_mfma_f32_16x16x32_bf16 v[36:39], v[166:169], v[198:201], v[36:39]
	v_mfma_f32_16x16x32_bf16 v[28:31], v[158:161], v[206:209], v[28:31]
	v_mfma_f32_16x16x32_bf16 v[20:23], v[166:169], v[206:209], v[20:23]
	v_mfma_f32_16x16x32_bf16 v[12:15], v[158:161], v[214:217], v[12:15]
	v_mfma_f32_16x16x32_bf16 v[4:7], v[166:169], v[214:217], v[4:7]
	s_setprio 0
	s_setprio 1
	v_mfma_f32_16x16x32_bf16 v[56:59], v[170:173], v[186:189], v[56:59]
	v_mfma_f32_16x16x32_bf16 v[48:51], v[178:181], v[186:189], v[48:51]
	v_mfma_f32_16x16x32_bf16 v[40:43], v[170:173], v[194:197], v[40:43]
	v_mfma_f32_16x16x32_bf16 v[32:35], v[178:181], v[194:197], v[32:35]
	v_mfma_f32_16x16x32_bf16 v[24:27], v[170:173], v[202:205], v[24:27]
	v_mfma_f32_16x16x32_bf16 v[16:19], v[178:181], v[202:205], v[16:19]
	v_mfma_f32_16x16x32_bf16 v[8:11], v[170:173], v[210:213], v[8:11]
	v_mfma_f32_16x16x32_bf16 v[0:3], v[178:181], v[210:213], v[0:3]
	v_mfma_f32_16x16x32_bf16 v[56:59], v[174:177], v[190:193], v[56:59]
	v_mfma_f32_16x16x32_bf16 v[48:51], v[182:185], v[190:193], v[48:51]
	v_mfma_f32_16x16x32_bf16 v[40:43], v[174:177], v[198:201], v[40:43]
	v_mfma_f32_16x16x32_bf16 v[32:35], v[182:185], v[198:201], v[32:35]
	v_mfma_f32_16x16x32_bf16 v[24:27], v[174:177], v[206:209], v[24:27]
	v_mfma_f32_16x16x32_bf16 v[16:19], v[182:185], v[206:209], v[16:19]
	v_mfma_f32_16x16x32_bf16 v[8:11], v[174:177], v[214:217], v[8:11]
	v_mfma_f32_16x16x32_bf16 v[0:3], v[182:185], v[214:217], v[0:3]
	s_barrier
	s_setprio 0
	s_add_i32 s63, 0, 0x18000
	s_add_i32 s64, 0, 0x1c000
	s_add_u32 s34, s34, 0x40000
	s_addc_u32 s35, s35, 0
	s_mov_b32 m0, s38
	v_lshl_add_u64 v[224:225], s[34:35], 0, v[134:135]
	global_load_lds_dwordx4 v[224:225], off
	v_lshl_add_u64 v[224:225], s[34:35], 0, v[130:131]
	s_mov_b32 m0, s39
	s_nop 0
	global_load_lds_dwordx4 v[224:225], off
	v_add_u32_e32 v153, s63, v147
	ds_read_b128 v[154:157], v153
	ds_read_b128 v[158:161], v153 offset:1024
	ds_read_b128 v[162:165], v153 offset:2048
	ds_read_b128 v[166:169], v153 offset:3072
	v_add_u32_e32 v153, s64, v147
	ds_read_b128 v[170:173], v153
	ds_read_b128 v[174:177], v153 offset:1024
	ds_read_b128 v[178:181], v153 offset:2048
	ds_read_b128 v[182:185], v153 offset:3072
	ds_read_b128 v[186:189], v151 offset:32768
	ds_read_b128 v[190:193], v151 offset:33792
	ds_read_b128 v[194:197], v151 offset:34816
	ds_read_b128 v[198:201], v151 offset:35840
	ds_read_b128 v[202:205], v151 offset:36864
	ds_read_b128 v[206:209], v151 offset:37888
	ds_read_b128 v[210:213], v151 offset:38912
	ds_read_b128 v[214:217], v151 offset:39936
	s_waitcnt vmcnt(8)
	s_waitcnt lgkmcnt(0)
	s_setprio 1
	s_barrier
	v_mfma_f32_16x16x32_bf16 v[116:119], v[154:157], v[186:189], v[116:119]
	v_mfma_f32_16x16x32_bf16 v[112:115], v[162:165], v[186:189], v[112:115]
	v_mfma_f32_16x16x32_bf16 v[108:111], v[154:157], v[194:197], v[108:111]
	v_mfma_f32_16x16x32_bf16 v[100:103], v[162:165], v[194:197], v[100:103]
	v_mfma_f32_16x16x32_bf16 v[92:95], v[154:157], v[202:205], v[92:95]
	v_mfma_f32_16x16x32_bf16 v[84:87], v[162:165], v[202:205], v[84:87]
	v_mfma_f32_16x16x32_bf16 v[76:79], v[154:157], v[210:213], v[76:79]
	v_mfma_f32_16x16x32_bf16 v[68:71], v[162:165], v[210:213], v[68:71]
	v_mfma_f32_16x16x32_bf16 v[116:119], v[158:161], v[190:193], v[116:119]
	v_mfma_f32_16x16x32_bf16 v[112:115], v[166:169], v[190:193], v[112:115]
	v_mfma_f32_16x16x32_bf16 v[108:111], v[158:161], v[198:201], v[108:111]
	v_mfma_f32_16x16x32_bf16 v[100:103], v[166:169], v[198:201], v[100:103]
	v_mfma_f32_16x16x32_bf16 v[92:95], v[158:161], v[206:209], v[92:95]
	v_mfma_f32_16x16x32_bf16 v[84:87], v[166:169], v[206:209], v[84:87]
	v_mfma_f32_16x16x32_bf16 v[76:79], v[158:161], v[214:217], v[76:79]
	v_mfma_f32_16x16x32_bf16 v[68:71], v[166:169], v[214:217], v[68:71]
	s_setprio 0
	s_setprio 1
	v_mfma_f32_16x16x32_bf16 v[124:127], v[170:173], v[186:189], v[124:127]
	v_mfma_f32_16x16x32_bf16 v[120:123], v[178:181], v[186:189], v[120:123]
	v_mfma_f32_16x16x32_bf16 v[104:107], v[170:173], v[194:197], v[104:107]
	v_mfma_f32_16x16x32_bf16 v[96:99], v[178:181], v[194:197], v[96:99]
	v_mfma_f32_16x16x32_bf16 v[88:91], v[170:173], v[202:205], v[88:91]
	v_mfma_f32_16x16x32_bf16 v[80:83], v[178:181], v[202:205], v[80:83]
	v_mfma_f32_16x16x32_bf16 v[72:75], v[170:173], v[210:213], v[72:75]
	v_mfma_f32_16x16x32_bf16 v[64:67], v[178:181], v[210:213], v[64:67]
	v_mfma_f32_16x16x32_bf16 v[124:127], v[174:177], v[190:193], v[124:127]
	v_mfma_f32_16x16x32_bf16 v[120:123], v[182:185], v[190:193], v[120:123]
	v_mfma_f32_16x16x32_bf16 v[104:107], v[174:177], v[198:201], v[104:107]
	v_mfma_f32_16x16x32_bf16 v[96:99], v[182:185], v[198:201], v[96:99]
	v_mfma_f32_16x16x32_bf16 v[88:91], v[174:177], v[206:209], v[88:91]
	v_mfma_f32_16x16x32_bf16 v[80:83], v[182:185], v[206:209], v[80:83]
	v_mfma_f32_16x16x32_bf16 v[72:75], v[174:177], v[214:217], v[72:75]
	v_mfma_f32_16x16x32_bf16 v[64:67], v[182:185], v[214:217], v[64:67]
	s_barrier
	s_setprio 0
	s_add_i32 s34, s63, s5
	v_lshl_add_u64 v[144:145], v[144:145], 0, s[12:13]
	s_mov_b32 m0, s34
	s_nop 0
	global_load_lds_dwordx4 v[144:145], off
	s_add_i32 m0, s34, 0x2000
	s_add_u32 s30, s30, 0x40080
	v_lshl_add_u64 v[144:145], v[218:219], 0, s[12:13]
	s_addc_u32 s31, s31, 0
	s_add_i32 s34, s64, s5
	global_load_lds_dwordx4 v[144:145], off
	v_lshl_add_u64 v[144:145], s[30:31], 0, v[132:133]
	s_mov_b32 m0, s34
	s_nop 0
	global_load_lds_dwordx4 v[144:145], off
	v_lshl_add_u64 v[144:145], s[30:31], 0, v[128:129]
	s_add_i32 m0, s34, 0x2000
	s_nop 0
	global_load_lds_dwordx4 v[144:145], off
	v_lshl_add_u64 v[144:145], v[220:221], 0, s[12:13]
	s_mov_b32 m0, s41
	s_nop 0
	global_load_lds_dwordx4 v[144:145], off
	v_lshl_add_u64 v[144:145], v[222:223], 0, s[12:13]
	s_mov_b32 m0, s42
	s_nop 0
	global_load_lds_dwordx4 v[144:145], off
	ds_read_b128 v[186:189], v151 offset:49152
	ds_read_b128 v[190:193], v151 offset:50176
	ds_read_b128 v[194:197], v151 offset:51200
	ds_read_b128 v[198:201], v151 offset:52224
	ds_read_b128 v[202:205], v151 offset:53248
	ds_read_b128 v[206:209], v151 offset:54272
	ds_read_b128 v[210:213], v151 offset:55296
	ds_read_b128 v[214:217], v151 offset:56320
	s_waitcnt vmcnt(8)
	s_waitcnt lgkmcnt(0)
	s_setprio 1
	s_barrier
	v_mfma_f32_16x16x32_bf16 v[60:63], v[154:157], v[186:189], v[60:63]
	v_mfma_f32_16x16x32_bf16 v[52:55], v[162:165], v[186:189], v[52:55]
	v_mfma_f32_16x16x32_bf16 v[44:47], v[154:157], v[194:197], v[44:47]
	v_mfma_f32_16x16x32_bf16 v[36:39], v[162:165], v[194:197], v[36:39]
	v_mfma_f32_16x16x32_bf16 v[28:31], v[154:157], v[202:205], v[28:31]
	v_mfma_f32_16x16x32_bf16 v[20:23], v[162:165], v[202:205], v[20:23]
	v_mfma_f32_16x16x32_bf16 v[12:15], v[154:157], v[210:213], v[12:15]
	v_mfma_f32_16x16x32_bf16 v[4:7], v[162:165], v[210:213], v[4:7]
	v_mfma_f32_16x16x32_bf16 v[60:63], v[158:161], v[190:193], v[60:63]
	v_mfma_f32_16x16x32_bf16 v[52:55], v[166:169], v[190:193], v[52:55]
	v_mfma_f32_16x16x32_bf16 v[44:47], v[158:161], v[198:201], v[44:47]
	v_mfma_f32_16x16x32_bf16 v[36:39], v[166:169], v[198:201], v[36:39]
	v_mfma_f32_16x16x32_bf16 v[28:31], v[158:161], v[206:209], v[28:31]
	v_mfma_f32_16x16x32_bf16 v[20:23], v[166:169], v[206:209], v[20:23]
	v_mfma_f32_16x16x32_bf16 v[12:15], v[158:161], v[214:217], v[12:15]
	v_mfma_f32_16x16x32_bf16 v[4:7], v[166:169], v[214:217], v[4:7]
	s_setprio 0
	s_setprio 1
	v_mfma_f32_16x16x32_bf16 v[56:59], v[170:173], v[186:189], v[56:59]
	v_mfma_f32_16x16x32_bf16 v[48:51], v[178:181], v[186:189], v[48:51]
	v_mfma_f32_16x16x32_bf16 v[40:43], v[170:173], v[194:197], v[40:43]
	v_mfma_f32_16x16x32_bf16 v[32:35], v[178:181], v[194:197], v[32:35]
	v_mfma_f32_16x16x32_bf16 v[24:27], v[170:173], v[202:205], v[24:27]
	v_mfma_f32_16x16x32_bf16 v[16:19], v[178:181], v[202:205], v[16:19]
	v_mfma_f32_16x16x32_bf16 v[8:11], v[170:173], v[210:213], v[8:11]
	v_mfma_f32_16x16x32_bf16 v[0:3], v[178:181], v[210:213], v[0:3]
	v_mfma_f32_16x16x32_bf16 v[56:59], v[174:177], v[190:193], v[56:59]
	v_mfma_f32_16x16x32_bf16 v[48:51], v[182:185], v[190:193], v[48:51]
	v_mfma_f32_16x16x32_bf16 v[40:43], v[174:177], v[198:201], v[40:43]
	v_mfma_f32_16x16x32_bf16 v[32:35], v[182:185], v[198:201], v[32:35]
	v_mfma_f32_16x16x32_bf16 v[24:27], v[174:177], v[206:209], v[24:27]
	v_mfma_f32_16x16x32_bf16 v[16:19], v[182:185], v[206:209], v[16:19]
	v_mfma_f32_16x16x32_bf16 v[8:11], v[174:177], v[214:217], v[8:11]
	v_mfma_f32_16x16x32_bf16 v[0:3], v[182:185], v[214:217], v[0:3]
	s_barrier
	s_setprio 0
	s_add_i32 s62, s62, 2
	s_add_u32 s28, s28, 0x100
	s_addc_u32 s29, s29, 0
	s_add_u32 s60, s60, 0x100
	s_addc_u32 s61, s61, 0
	s_cmp_gt_u32 s62, 13
	s_cbranch_scc0 .LBB0_1193
	s_and_b64 vcc, exec, s[14:15]
	s_cbranch_vccz .LBB0_1196
	s_barrier

.LBB0_1218:
	s_or_b64 exec, exec, s[12:13]
	v_cvt_f32_u32_e32 v4, v2
	s_waitcnt vmcnt(0)
	v_readfirstlane_b32 s2, v3
	v_sub_u32_e32 v3, 0, v2
	v_rcp_iflag_f32_e32 v4, v4
	v_add_u32_e32 v5, s2, v1
	v_mul_f32_e32 v4, 0x4f7ffffe, v4
	v_cvt_u32_f32_e32 v4, v4
	v_mul_lo_u32 v1, v3, v4
	v_mul_hi_u32 v1, v4, v1
	v_add_u32_e32 v1, v4, v1
	v_mul_hi_u32 v1, v5, v1
	v_mul_lo_u32 v3, v1, v2
	v_sub_u32_e32 v3, v5, v3
	v_add_u32_e32 v4, 1, v1
	v_cmp_ge_u32_e32 vcc, v3, v2
	s_nop 1
	v_cndmask_b32_e32 v1, v1, v4, vcc
	v_sub_u32_e32 v4, v3, v2
	v_cndmask_b32_e32 v3, v3, v4, vcc
	v_add_u32_e32 v4, 1, v1
	v_cmp_ge_u32_e32 vcc, v3, v2
	v_add_u32_e32 v3, 1, v5
	s_nop 0
	v_cndmask_b32_e32 v1, v1, v4, vcc
	v_mul_lo_u32 v4, v2, v1
	v_add_u32_e32 v2, v4, v2
	v_cmp_ne_u32_e32 vcc, v3, v2
	s_and_saveexec_b64 s[2:3], vcc
	s_xor_b64 s[10:11], exec, s[2:3]
	s_cbranch_execz .LBB0_1232
	s_waitcnt lgkmcnt(0)
	v_mad_u32_u24 v3, v1, v0, v0
	v_mov_b32_e32 v0, 0x3000
	global_load_dword v0, v0, s[54:55] offset:1024 sc1
	s_add_u32 s14, s54, 0x3400
	s_addc_u32 s15, s55, 0
	s_waitcnt vmcnt(0)
	v_cmp_lt_u32_e32 vcc, v0, v3
	s_and_saveexec_b64 s[12:13], vcc
	s_cbranch_execz .LBB0_1231
	s_mov_b32 s2, 1
	s_mov_b64 s[16:17], 0
	v_mov_b32_e32 v0, 0
	s_branch .LBB0_1222

.Lph1273_w:
	s_nop 0
	s_nop 0
	s_nop 0
	s_waitcnt vmcnt(8)
	s_waitcnt lgkmcnt(0)
	s_setprio 1
	s_barrier
	v_mfma_f32_16x16x32_bf16 v[124:127], v[128:131], v[160:163], v[124:127]
	v_mfma_f32_16x16x32_bf16 v[120:123], v[136:139], v[160:163], v[120:123]
	v_mfma_f32_16x16x32_bf16 v[112:115], v[128:131], v[184:187], v[112:115]
	v_mfma_f32_16x16x32_bf16 v[104:107], v[136:139], v[184:187], v[104:107]
	v_mfma_f32_16x16x32_bf16 v[96:99], v[128:131], v[200:203], v[96:99]
	v_mfma_f32_16x16x32_bf16 v[88:91], v[136:139], v[200:203], v[88:91]
	v_mfma_f32_16x16x32_bf16 v[80:83], v[128:131], v[208:211], v[80:83]
	v_mfma_f32_16x16x32_bf16 v[72:75], v[136:139], v[208:211], v[72:75]
	v_mfma_f32_16x16x32_bf16 v[124:127], v[132:135], v[180:183], v[124:127]
	v_mfma_f32_16x16x32_bf16 v[120:123], v[140:143], v[180:183], v[120:123]
	v_mfma_f32_16x16x32_bf16 v[112:115], v[132:135], v[188:191], v[112:115]
	v_mfma_f32_16x16x32_bf16 v[104:107], v[140:143], v[188:191], v[104:107]
	v_mfma_f32_16x16x32_bf16 v[96:99], v[132:135], v[204:207], v[96:99]
	v_mfma_f32_16x16x32_bf16 v[88:91], v[140:143], v[204:207], v[88:91]
	v_mfma_f32_16x16x32_bf16 v[80:83], v[132:135], v[212:215], v[80:83]
	v_mfma_f32_16x16x32_bf16 v[72:75], v[140:143], v[212:215], v[72:75]
	s_setprio 0
	s_setprio 1
	v_mfma_f32_16x16x32_bf16 v[116:119], v[144:147], v[160:163], v[116:119]
	v_mfma_f32_16x16x32_bf16 v[108:111], v[152:155], v[160:163], v[108:111]
	v_mfma_f32_16x16x32_bf16 v[100:103], v[144:147], v[184:187], v[100:103]
	v_mfma_f32_16x16x32_bf16 v[92:95], v[152:155], v[184:187], v[92:95]
	v_mfma_f32_16x16x32_bf16 v[84:87], v[144:147], v[200:203], v[84:87]
	v_mfma_f32_16x16x32_bf16 v[76:79], v[152:155], v[200:203], v[76:79]
	v_mfma_f32_16x16x32_bf16 v[68:71], v[144:147], v[208:211], v[68:71]
	v_mfma_f32_16x16x32_bf16 v[64:67], v[152:155], v[208:211], v[64:67]
	v_mfma_f32_16x16x32_bf16 v[116:119], v[148:151], v[180:183], v[116:119]
	v_mfma_f32_16x16x32_bf16 v[108:111], v[156:159], v[180:183], v[108:111]
	v_mfma_f32_16x16x32_bf16 v[100:103], v[148:151], v[188:191], v[100:103]
	v_mfma_f32_16x16x32_bf16 v[92:95], v[156:159], v[188:191], v[92:95]
	v_mfma_f32_16x16x32_bf16 v[84:87], v[148:151], v[204:207], v[84:87]
	v_mfma_f32_16x16x32_bf16 v[76:79], v[156:159], v[204:207], v[76:79]
	v_mfma_f32_16x16x32_bf16 v[68:71], v[148:151], v[212:215], v[68:71]
	v_mfma_f32_16x16x32_bf16 v[64:67], v[156:159], v[212:215], v[64:67]
	s_barrier
	s_setprio 0
	s_add_i32 s16, s38, s25
	v_lshl_add_u64 v[192:193], s[20:21], 0, v[166:167]
	s_mov_b32 m0, s16
	s_nop 0
	global_load_lds_dwordx4 v[192:193], off
	s_add_i32 m0, s16, 0x2000
	s_add_u32 s16, s20, 0xb0000
	v_lshl_add_u64 v[216:217], s[20:21], 0, v[170:171]
	s_addc_u32 s17, s21, 0
	s_add_i32 s47, s39, s25
	global_load_lds_dwordx4 v[216:217], off
	v_lshl_add_u64 v[218:219], s[16:17], 0, v[166:167]
	s_mov_b32 m0, s47
	v_lshl_add_u64 v[220:221], s[22:23], 0, v[168:169]
	global_load_lds_dwordx4 v[218:219], off
	v_lshl_add_u64 v[218:219], s[16:17], 0, v[170:171]
	s_add_i32 m0, s47, 0x2000
	s_nop 0
	global_load_lds_dwordx4 v[218:219], off
	v_lshl_add_u64 v[218:219], s[22:23], 0, v[164:165]
	s_mov_b32 m0, s26
	s_nop 0
	global_load_lds_dwordx4 v[218:219], off
	s_mov_b32 m0, s27
	s_nop 0
	global_load_lds_dwordx4 v[220:221], off
	ds_read_b128 v[160:163], v199 offset:16384
	ds_read_b128 v[180:183], v199 offset:17408
	ds_read_b128 v[184:187], v199 offset:18432
	ds_read_b128 v[188:191], v199 offset:19456
	ds_read_b128 v[200:203], v199 offset:20480
	ds_read_b128 v[204:207], v199 offset:21504
	ds_read_b128 v[208:211], v199 offset:22528
	ds_read_b128 v[212:215], v199 offset:23552
	s_nop 0
	s_waitcnt vmcnt(8)
	s_waitcnt lgkmcnt(0)
	s_setprio 1
	s_barrier
	v_mfma_f32_16x16x32_bf16 v[60:63], v[128:131], v[160:163], v[60:63]
	v_mfma_f32_16x16x32_bf16 v[56:59], v[136:139], v[160:163], v[56:59]
	v_mfma_f32_16x16x32_bf16 v[48:51], v[128:131], v[184:187], v[48:51]
	v_mfma_f32_16x16x32_bf16 v[40:43], v[136:139], v[184:187], v[40:43]
	v_mfma_f32_16x16x32_bf16 v[32:35], v[128:131], v[200:203], v[32:35]
	v_mfma_f32_16x16x32_bf16 v[24:27], v[136:139], v[200:203], v[24:27]
	v_mfma_f32_16x16x32_bf16 v[16:19], v[128:131], v[208:211], v[16:19]
	v_mfma_f32_16x16x32_bf16 v[8:11], v[136:139], v[208:211], v[8:11]
	v_mfma_f32_16x16x32_bf16 v[60:63], v[132:135], v[180:183], v[60:63]
	v_mfma_f32_16x16x32_bf16 v[56:59], v[140:143], v[180:183], v[56:59]
	v_mfma_f32_16x16x32_bf16 v[48:51], v[132:135], v[188:191], v[48:51]
	v_mfma_f32_16x16x32_bf16 v[40:43], v[140:143], v[188:191], v[40:43]
	v_mfma_f32_16x16x32_bf16 v[32:35], v[132:135], v[204:207], v[32:35]
	v_mfma_f32_16x16x32_bf16 v[24:27], v[140:143], v[204:207], v[24:27]
	v_mfma_f32_16x16x32_bf16 v[16:19], v[132:135], v[212:215], v[16:19]
	v_mfma_f32_16x16x32_bf16 v[8:11], v[140:143], v[212:215], v[8:11]
	s_setprio 0
	s_setprio 1
	v_mfma_f32_16x16x32_bf16 v[52:55], v[144:147], v[160:163], v[52:55]
	v_mfma_f32_16x16x32_bf16 v[44:47], v[152:155], v[160:163], v[44:47]
	v_mfma_f32_16x16x32_bf16 v[36:39], v[144:147], v[184:187], v[36:39]
	v_mfma_f32_16x16x32_bf16 v[28:31], v[152:155], v[184:187], v[28:31]
	v_mfma_f32_16x16x32_bf16 v[20:23], v[144:147], v[200:203], v[20:23]
	v_mfma_f32_16x16x32_bf16 v[12:15], v[152:155], v[200:203], v[12:15]
	v_mfma_f32_16x16x32_bf16 v[4:7], v[144:147], v[208:211], v[4:7]
	v_mfma_f32_16x16x32_bf16 v[0:3], v[152:155], v[208:211], v[0:3]
	v_mfma_f32_16x16x32_bf16 v[52:55], v[148:151], v[180:183], v[52:55]
	v_mfma_f32_16x16x32_bf16 v[44:47], v[156:159], v[180:183], v[44:47]
	v_mfma_f32_16x16x32_bf16 v[36:39], v[148:151], v[188:191], v[36:39]
	v_mfma_f32_16x16x32_bf16 v[28:31], v[156:159], v[188:191], v[28:31]
	v_mfma_f32_16x16x32_bf16 v[20:23], v[148:151], v[204:207], v[20:23]
	v_mfma_f32_16x16x32_bf16 v[12:15], v[156:159], v[204:207], v[12:15]
	v_mfma_f32_16x16x32_bf16 v[4:7], v[148:151], v[212:215], v[4:7]
	v_mfma_f32_16x16x32_bf16 v[0:3], v[156:159], v[212:215], v[0:3]
	s_barrier
	s_setprio 0
	s_add_i32 s47, 0, 0x18000
	s_add_i32 s48, 0, 0x1c000
	s_add_u32 s16, s22, 0xb0000
	s_addc_u32 s17, s23, 0
	s_mov_b32 m0, s28
	v_lshl_add_u64 v[222:223], s[16:17], 0, v[164:165]
	global_load_lds_dwordx4 v[222:223], off
	v_lshl_add_u64 v[222:223], s[16:17], 0, v[168:169]
	s_mov_b32 m0, s29
	s_nop 0
	global_load_lds_dwordx4 v[222:223], off
	v_add_u32_e32 v140, s47, v196
	v_add_u32_e32 v156, s48, v196
	ds_read_b128 v[128:131], v140
	ds_read_b128 v[132:135], v140 offset:1024
	ds_read_b128 v[136:139], v140 offset:2048
	ds_read_b128 v[140:143], v140 offset:3072
	ds_read_b128 v[144:147], v156
	ds_read_b128 v[148:151], v156 offset:1024
	ds_read_b128 v[152:155], v156 offset:2048
	ds_read_b128 v[156:159], v156 offset:3072
	ds_read_b128 v[160:163], v199 offset:32768
	ds_read_b128 v[180:183], v199 offset:33792
	ds_read_b128 v[184:187], v199 offset:34816
	ds_read_b128 v[188:191], v199 offset:35840
	ds_read_b128 v[200:203], v199 offset:36864
	ds_read_b128 v[204:207], v199 offset:37888
	ds_read_b128 v[208:211], v199 offset:38912
	ds_read_b128 v[212:215], v199 offset:39936
	s_waitcnt vmcnt(8)
	s_waitcnt lgkmcnt(0)
	s_setprio 1
	s_barrier
	v_mfma_f32_16x16x32_bf16 v[124:127], v[128:131], v[160:163], v[124:127]
	v_mfma_f32_16x16x32_bf16 v[120:123], v[136:139], v[160:163], v[120:123]
	v_mfma_f32_16x16x32_bf16 v[112:115], v[128:131], v[184:187], v[112:115]
	v_mfma_f32_16x16x32_bf16 v[104:107], v[136:139], v[184:187], v[104:107]
	v_mfma_f32_16x16x32_bf16 v[96:99], v[128:131], v[200:203], v[96:99]
	v_mfma_f32_16x16x32_bf16 v[88:91], v[136:139], v[200:203], v[88:91]
	v_mfma_f32_16x16x32_bf16 v[80:83], v[128:131], v[208:211], v[80:83]
	v_mfma_f32_16x16x32_bf16 v[72:75], v[136:139], v[208:211], v[72:75]
	v_mfma_f32_16x16x32_bf16 v[124:127], v[132:135], v[180:183], v[124:127]
	v_mfma_f32_16x16x32_bf16 v[120:123], v[140:143], v[180:183], v[120:123]
	v_mfma_f32_16x16x32_bf16 v[112:115], v[132:135], v[188:191], v[112:115]
	v_mfma_f32_16x16x32_bf16 v[104:107], v[140:143], v[188:191], v[104:107]
	v_mfma_f32_16x16x32_bf16 v[96:99], v[132:135], v[204:207], v[96:99]
	v_mfma_f32_16x16x32_bf16 v[88:91], v[140:143], v[204:207], v[88:91]
	v_mfma_f32_16x16x32_bf16 v[80:83], v[132:135], v[212:215], v[80:83]
	v_mfma_f32_16x16x32_bf16 v[72:75], v[140:143], v[212:215], v[72:75]
	s_setprio 0
	s_setprio 1
	v_mfma_f32_16x16x32_bf16 v[116:119], v[144:147], v[160:163], v[116:119]
	v_mfma_f32_16x16x32_bf16 v[108:111], v[152:155], v[160:163], v[108:111]
	v_mfma_f32_16x16x32_bf16 v[100:103], v[144:147], v[184:187], v[100:103]
	v_mfma_f32_16x16x32_bf16 v[92:95], v[152:155], v[184:187], v[92:95]
	v_mfma_f32_16x16x32_bf16 v[84:87], v[144:147], v[200:203], v[84:87]
	v_mfma_f32_16x16x32_bf16 v[76:79], v[152:155], v[200:203], v[76:79]
	v_mfma_f32_16x16x32_bf16 v[68:71], v[144:147], v[208:211], v[68:71]
	v_mfma_f32_16x16x32_bf16 v[64:67], v[152:155], v[208:211], v[64:67]
	v_mfma_f32_16x16x32_bf16 v[116:119], v[148:151], v[180:183], v[116:119]
	v_mfma_f32_16x16x32_bf16 v[108:111], v[156:159], v[180:183], v[108:111]
	v_mfma_f32_16x16x32_bf16 v[100:103], v[148:151], v[188:191], v[100:103]
	v_mfma_f32_16x16x32_bf16 v[92:95], v[156:159], v[188:191], v[92:95]
	v_mfma_f32_16x16x32_bf16 v[84:87], v[148:151], v[204:207], v[84:87]
	v_mfma_f32_16x16x32_bf16 v[76:79], v[156:159], v[204:207], v[76:79]
	v_mfma_f32_16x16x32_bf16 v[68:71], v[148:151], v[212:215], v[68:71]
	v_mfma_f32_16x16x32_bf16 v[64:67], v[156:159], v[212:215], v[64:67]
	s_barrier
	s_setprio 0
	s_add_i32 s16, s47, s25
	v_lshl_add_u64 v[192:193], v[192:193], 0, s[10:11]
	s_mov_b32 m0, s16
	s_nop 0
	global_load_lds_dwordx4 v[192:193], off
	s_add_i32 m0, s16, 0x2000
	s_add_u32 s16, s20, 0xb0080
	v_lshl_add_u64 v[192:193], v[216:217], 0, s[10:11]
	s_addc_u32 s17, s21, 0
	s_add_i32 s20, s48, s25
	global_load_lds_dwordx4 v[192:193], off
	v_lshl_add_u64 v[192:193], s[16:17], 0, v[166:167]
	s_mov_b32 m0, s20
	s_nop 0
	global_load_lds_dwordx4 v[192:193], off
	v_lshl_add_u64 v[192:193], s[16:17], 0, v[170:171]
	s_add_i32 m0, s20, 0x2000
	s_nop 0
	global_load_lds_dwordx4 v[192:193], off
	v_lshl_add_u64 v[192:193], v[218:219], 0, s[10:11]
	s_mov_b32 m0, s35
	s_nop 0
	global_load_lds_dwordx4 v[192:193], off
	v_lshl_add_u64 v[192:193], v[220:221], 0, s[10:11]
	s_mov_b32 m0, s36
	s_nop 0
	global_load_lds_dwordx4 v[192:193], off
	ds_read_b128 v[160:163], v199 offset:49152
	ds_read_b128 v[180:183], v199 offset:50176
	ds_read_b128 v[184:187], v199 offset:51200
	ds_read_b128 v[188:191], v199 offset:52224
	ds_read_b128 v[200:203], v199 offset:53248
	ds_read_b128 v[204:207], v199 offset:54272
	ds_read_b128 v[208:211], v199 offset:55296
	ds_read_b128 v[212:215], v199 offset:56320
	s_waitcnt vmcnt(8)
	s_waitcnt lgkmcnt(0)
	s_setprio 1
	s_barrier
	v_mfma_f32_16x16x32_bf16 v[60:63], v[128:131], v[160:163], v[60:63]
	v_mfma_f32_16x16x32_bf16 v[56:59], v[136:139], v[160:163], v[56:59]
	v_mfma_f32_16x16x32_bf16 v[48:51], v[128:131], v[184:187], v[48:51]
	v_mfma_f32_16x16x32_bf16 v[40:43], v[136:139], v[184:187], v[40:43]
	v_mfma_f32_16x16x32_bf16 v[32:35], v[128:131], v[200:203], v[32:35]
	v_mfma_f32_16x16x32_bf16 v[24:27], v[136:139], v[200:203], v[24:27]
	v_mfma_f32_16x16x32_bf16 v[16:19], v[128:131], v[208:211], v[16:19]
	v_mfma_f32_16x16x32_bf16 v[8:11], v[136:139], v[208:211], v[8:11]
	v_mfma_f32_16x16x32_bf16 v[60:63], v[132:135], v[180:183], v[60:63]
	v_mfma_f32_16x16x32_bf16 v[56:59], v[140:143], v[180:183], v[56:59]
	v_mfma_f32_16x16x32_bf16 v[48:51], v[132:135], v[188:191], v[48:51]
	v_mfma_f32_16x16x32_bf16 v[40:43], v[140:143], v[188:191], v[40:43]
	v_mfma_f32_16x16x32_bf16 v[32:35], v[132:135], v[204:207], v[32:35]
	v_mfma_f32_16x16x32_bf16 v[24:27], v[140:143], v[204:207], v[24:27]
	v_mfma_f32_16x16x32_bf16 v[16:19], v[132:135], v[212:215], v[16:19]
	v_mfma_f32_16x16x32_bf16 v[8:11], v[140:143], v[212:215], v[8:11]
	s_setprio 0
	s_setprio 1
	v_mfma_f32_16x16x32_bf16 v[52:55], v[144:147], v[160:163], v[52:55]
	v_mfma_f32_16x16x32_bf16 v[44:47], v[152:155], v[160:163], v[44:47]
	v_mfma_f32_16x16x32_bf16 v[36:39], v[144:147], v[184:187], v[36:39]
	v_mfma_f32_16x16x32_bf16 v[28:31], v[152:155], v[184:187], v[28:31]
	v_mfma_f32_16x16x32_bf16 v[20:23], v[144:147], v[200:203], v[20:23]
	v_mfma_f32_16x16x32_bf16 v[12:15], v[152:155], v[200:203], v[12:15]
	v_mfma_f32_16x16x32_bf16 v[4:7], v[144:147], v[208:211], v[4:7]
	v_mfma_f32_16x16x32_bf16 v[0:3], v[152:155], v[208:211], v[0:3]
	v_mfma_f32_16x16x32_bf16 v[52:55], v[148:151], v[180:183], v[52:55]
	v_mfma_f32_16x16x32_bf16 v[44:47], v[156:159], v[180:183], v[44:47]
	v_mfma_f32_16x16x32_bf16 v[36:39], v[148:151], v[188:191], v[36:39]
	v_mfma_f32_16x16x32_bf16 v[28:31], v[156:159], v[188:191], v[28:31]
	v_mfma_f32_16x16x32_bf16 v[20:23], v[148:151], v[204:207], v[20:23]
	v_mfma_f32_16x16x32_bf16 v[12:15], v[156:159], v[204:207], v[12:15]
	v_mfma_f32_16x16x32_bf16 v[4:7], v[148:151], v[212:215], v[4:7]
	v_mfma_f32_16x16x32_bf16 v[0:3], v[156:159], v[212:215], v[0:3]
	s_barrier
	s_setprio 0
	s_add_i32 s46, s46, 2
	s_add_u32 s44, s44, 0x100
	s_addc_u32 s45, s45, 0
	s_cmp_gt_u32 s46, 41
	s_mov_b64 s[16:17], s[18:19]
	s_cbranch_scc0 .LBB0_1273
	s_and_b64 vcc, exec, s[12:13]
	s_cbranch_vccz .LBB0_1276
	s_barrier
